# cv32 + GEMM K-loops: LDS-DMA operand loads use the scalar-base form (v_off, s[base]) so the 16 per-iteration 64-bit VALU address adds leave the load segments; two scalar temporaries (s98:99, s100:101)
# speedup vs baseline: 1.0074x; 1.0074x over previous
.LBB0_306:
	s_add_u32 s38, s36, 0xfff80080
	s_addc_u32 s39, s37, -1
	s_add_i32 s45, 0, 0x10000
	s_cmp_eq_u32 s27, 28
	s_cselect_b32 s43, s9, s39
	s_cselect_b32 s42, s14, s38
	v_add_u32_e32 v34, s45, v170
	s_cselect_b32 s39, s16, s26
	s_cselect_b32 s38, s17, s25
	s_add_i32 s47, 0, 0x14000
	ds_read_b128 v[160:163], v34
	ds_read_b128 v[164:167], v34 offset:1024
	ds_read_b128 v[174:177], v34 offset:2048
	ds_read_b128 v[184:187], v34 offset:3072
	v_add_u32_e32 v34, s47, v170
	ds_read_b128 v[188:191], v34
	ds_read_b128 v[192:195], v34 offset:1024
	ds_read_b128 v[196:199], v34 offset:2048
	ds_read_b128 v[200:203], v34 offset:3072
	s_add_i32 m0, s35, 0xc000
	ds_read_b128 v[214:217], v173
	ds_read_b128 v[218:221], v173 offset:1024
	ds_read_b128 v[222:225], v173 offset:2048
	ds_read_b128 v[226:229], v173 offset:3072
	ds_read_b128 v[230:233], v173 offset:4096
	ds_read_b128 v[234:237], v173 offset:5120
	ds_read_b128 v[238:241], v173 offset:6144
	ds_read_b128 v[242:245], v173 offset:7168
	global_load_lds_dwordx4 v152, s[36:37]
	s_add_i32 m0, s35, 0xe000
	s_nop 0
	global_load_lds_dwordx4 v156, s[36:37]
	s_waitcnt vmcnt(8)
	s_waitcnt lgkmcnt(0)
	s_barrier
	s_setprio 1
	s_waitcnt lgkmcnt(0)
	v_mfma_f32_16x16x32_bf16 v[132:135], v[160:163], v[214:217], v[132:135]
	v_mfma_f32_16x16x32_bf16 v[128:131], v[174:177], v[214:217], v[128:131]
	v_mfma_f32_16x16x32_bf16 v[116:119], v[160:163], v[222:225], v[116:119]
	v_mfma_f32_16x16x32_bf16 v[112:115], v[174:177], v[222:225], v[112:115]
	v_mfma_f32_16x16x32_bf16 v[100:103], v[160:163], v[230:233], v[100:103]
	v_mfma_f32_16x16x32_bf16 v[96:99], v[174:177], v[230:233], v[96:99]
	v_mfma_f32_16x16x32_bf16 v[84:87], v[160:163], v[238:241], v[84:87]
	v_mfma_f32_16x16x32_bf16 v[80:83], v[174:177], v[238:241], v[80:83]
	v_mfma_f32_16x16x32_bf16 v[132:135], v[164:167], v[218:221], v[132:135]
	v_mfma_f32_16x16x32_bf16 v[128:131], v[184:187], v[218:221], v[128:131]
	v_mfma_f32_16x16x32_bf16 v[116:119], v[164:167], v[226:229], v[116:119]
	v_mfma_f32_16x16x32_bf16 v[112:115], v[184:187], v[226:229], v[112:115]
	v_mfma_f32_16x16x32_bf16 v[100:103], v[164:167], v[234:237], v[100:103]
	v_mfma_f32_16x16x32_bf16 v[96:99], v[184:187], v[234:237], v[96:99]
	v_mfma_f32_16x16x32_bf16 v[84:87], v[164:167], v[242:245], v[84:87]
	v_mfma_f32_16x16x32_bf16 v[80:83], v[184:187], v[242:245], v[80:83]
	s_setprio 0
	s_setprio 1
	v_mfma_f32_16x16x32_bf16 v[124:127], v[188:191], v[214:217], v[124:127]
	v_mfma_f32_16x16x32_bf16 v[120:123], v[196:199], v[214:217], v[120:123]
	v_mfma_f32_16x16x32_bf16 v[108:111], v[188:191], v[222:225], v[108:111]
	v_mfma_f32_16x16x32_bf16 v[104:107], v[196:199], v[222:225], v[104:107]
	v_mfma_f32_16x16x32_bf16 v[92:95], v[188:191], v[230:233], v[92:95]
	v_mfma_f32_16x16x32_bf16 v[88:91], v[196:199], v[230:233], v[88:91]
	v_mfma_f32_16x16x32_bf16 v[76:79], v[188:191], v[238:241], v[76:79]
	v_mfma_f32_16x16x32_bf16 v[72:75], v[196:199], v[238:241], v[72:75]
	v_mfma_f32_16x16x32_bf16 v[124:127], v[192:195], v[218:221], v[124:127]
	v_mfma_f32_16x16x32_bf16 v[120:123], v[200:203], v[218:221], v[120:123]
	v_mfma_f32_16x16x32_bf16 v[108:111], v[192:195], v[226:229], v[108:111]
	v_mfma_f32_16x16x32_bf16 v[104:107], v[200:203], v[226:229], v[104:107]
	v_mfma_f32_16x16x32_bf16 v[92:95], v[192:195], v[234:237], v[92:95]
	v_mfma_f32_16x16x32_bf16 v[88:91], v[200:203], v[234:237], v[88:91]
	v_mfma_f32_16x16x32_bf16 v[76:79], v[192:195], v[242:245], v[76:79]
	v_mfma_f32_16x16x32_bf16 v[72:75], v[200:203], v[242:245], v[72:75]
	s_setprio 0
	s_barrier
	s_add_u32 s98, s38, s22
	s_addc_u32 s99, s39, s23
	s_add_u32 s100, s42, s22
	s_addc_u32 s101, s43, s23
	s_add_i32 s45, s45, s53
	s_mov_b32 m0, s45
	ds_read_b128 v[214:217], v173 offset:16384
	ds_read_b128 v[218:221], v173 offset:17408
	ds_read_b128 v[222:225], v173 offset:18432
	ds_read_b128 v[226:229], v173 offset:19456
	ds_read_b128 v[230:233], v173 offset:20480
	ds_read_b128 v[234:237], v173 offset:21504
	ds_read_b128 v[238:241], v173 offset:22528
	ds_read_b128 v[242:245], v173 offset:23552
	global_load_lds_dwordx4 v136, s[38:39]
	s_add_i32 m0, s45, 0x2000
	s_add_u32 s70, s38, 0x80000
	s_addc_u32 s71, s39, 0
	s_add_i32 s45, s47, s53
	global_load_lds_dwordx4 v140, s[38:39]
	s_mov_b32 m0, s45
	global_load_lds_dwordx4 v136, s[70:71]
	s_add_i32 m0, s45, 0x2000
	s_nop 0
	global_load_lds_dwordx4 v140, s[70:71]
	s_mov_b32 m0, s35
	s_nop 0
	global_load_lds_dwordx4 v14, s[42:43]
	s_mov_b32 m0, s54
	s_nop 0
	global_load_lds_dwordx4 v138, s[42:43]
	s_waitcnt vmcnt(8)
	s_waitcnt lgkmcnt(0)
	s_barrier
	s_setprio 1
	s_waitcnt lgkmcnt(0)
	v_mfma_f32_16x16x32_bf16 v[68:71], v[160:163], v[214:217], v[68:71]
	v_mfma_f32_16x16x32_bf16 v[64:67], v[174:177], v[214:217], v[64:67]
	v_mfma_f32_16x16x32_bf16 v[52:55], v[160:163], v[222:225], v[52:55]
	v_mfma_f32_16x16x32_bf16 v[48:51], v[174:177], v[222:225], v[48:51]
	v_mfma_f32_16x16x32_bf16 v[36:39], v[160:163], v[230:233], v[36:39]
	v_mfma_f32_16x16x32_bf16 v[30:33], v[174:177], v[230:233], v[30:33]
	v_mfma_f32_16x16x32_bf16 v[18:21], v[160:163], v[238:241], v[18:21]
	v_mfma_f32_16x16x32_bf16 v[10:13], v[174:177], v[238:241], v[10:13]
	v_mfma_f32_16x16x32_bf16 v[68:71], v[164:167], v[218:221], v[68:71]
	v_mfma_f32_16x16x32_bf16 v[64:67], v[184:187], v[218:221], v[64:67]
	v_mfma_f32_16x16x32_bf16 v[52:55], v[164:167], v[226:229], v[52:55]
	v_mfma_f32_16x16x32_bf16 v[48:51], v[184:187], v[226:229], v[48:51]
	v_mfma_f32_16x16x32_bf16 v[36:39], v[164:167], v[234:237], v[36:39]
	v_mfma_f32_16x16x32_bf16 v[30:33], v[184:187], v[234:237], v[30:33]
	v_mfma_f32_16x16x32_bf16 v[18:21], v[164:167], v[242:245], v[18:21]
	v_mfma_f32_16x16x32_bf16 v[10:13], v[184:187], v[242:245], v[10:13]
	s_setprio 0
	s_setprio 1
	v_mfma_f32_16x16x32_bf16 v[60:63], v[188:191], v[214:217], v[60:63]
	v_mfma_f32_16x16x32_bf16 v[56:59], v[196:199], v[214:217], v[56:59]
	v_mfma_f32_16x16x32_bf16 v[44:47], v[188:191], v[222:225], v[44:47]
	v_mfma_f32_16x16x32_bf16 v[40:43], v[196:199], v[222:225], v[40:43]
	v_mfma_f32_16x16x32_bf16 v[26:29], v[188:191], v[230:233], v[26:29]
	v_mfma_f32_16x16x32_bf16 v[22:25], v[196:199], v[230:233], v[22:25]
	v_mfma_f32_16x16x32_bf16 v[6:9], v[188:191], v[238:241], v[6:9]
	v_mfma_f32_16x16x32_bf16 v[2:5], v[196:199], v[238:241], v[2:5]
	v_mfma_f32_16x16x32_bf16 v[60:63], v[192:195], v[218:221], v[60:63]
	v_mfma_f32_16x16x32_bf16 v[56:59], v[200:203], v[218:221], v[56:59]
	v_mfma_f32_16x16x32_bf16 v[44:47], v[192:195], v[226:229], v[44:47]
	v_mfma_f32_16x16x32_bf16 v[40:43], v[200:203], v[226:229], v[40:43]
	v_mfma_f32_16x16x32_bf16 v[26:29], v[192:195], v[234:237], v[26:29]
	v_mfma_f32_16x16x32_bf16 v[22:25], v[200:203], v[234:237], v[22:25]
	v_mfma_f32_16x16x32_bf16 v[6:9], v[192:195], v[242:245], v[6:9]
	v_mfma_f32_16x16x32_bf16 v[2:5], v[200:203], v[242:245], v[2:5]
	s_setprio 0
	s_barrier
	s_add_i32 s45, 0, 0x18000
	v_add_u32_e32 v34, s45, v170
	s_add_i32 s47, 0, 0x1c000
	ds_read_b128 v[160:163], v34
	ds_read_b128 v[164:167], v34 offset:1024
	ds_read_b128 v[174:177], v34 offset:2048
	ds_read_b128 v[184:187], v34 offset:3072
	v_add_u32_e32 v34, s47, v170
	ds_read_b128 v[188:191], v34
	ds_read_b128 v[192:195], v34 offset:1024
	ds_read_b128 v[196:199], v34 offset:2048
	ds_read_b128 v[200:203], v34 offset:3072
	s_add_u32 s42, s42, 0x80000
	s_addc_u32 s43, s43, 0
	s_mov_b32 m0, s55
	ds_read_b128 v[214:217], v173 offset:32768
	ds_read_b128 v[218:221], v173 offset:33792
	ds_read_b128 v[222:225], v173 offset:34816
	ds_read_b128 v[226:229], v173 offset:35840
	ds_read_b128 v[230:233], v173 offset:36864
	ds_read_b128 v[234:237], v173 offset:37888
	ds_read_b128 v[238:241], v173 offset:38912
	ds_read_b128 v[242:245], v173 offset:39936
	global_load_lds_dwordx4 v14, s[42:43]
	s_mov_b32 m0, s60
	s_nop 0
	global_load_lds_dwordx4 v138, s[42:43]
	s_waitcnt vmcnt(8)
	s_waitcnt lgkmcnt(0)
	s_barrier
	s_setprio 1
	s_waitcnt lgkmcnt(0)
	v_mfma_f32_16x16x32_bf16 v[132:135], v[160:163], v[214:217], v[132:135]
	v_mfma_f32_16x16x32_bf16 v[128:131], v[174:177], v[214:217], v[128:131]
	v_mfma_f32_16x16x32_bf16 v[116:119], v[160:163], v[222:225], v[116:119]
	v_mfma_f32_16x16x32_bf16 v[112:115], v[174:177], v[222:225], v[112:115]
	v_mfma_f32_16x16x32_bf16 v[100:103], v[160:163], v[230:233], v[100:103]
	v_mfma_f32_16x16x32_bf16 v[96:99], v[174:177], v[230:233], v[96:99]
	v_mfma_f32_16x16x32_bf16 v[84:87], v[160:163], v[238:241], v[84:87]
	v_mfma_f32_16x16x32_bf16 v[80:83], v[174:177], v[238:241], v[80:83]
	v_mfma_f32_16x16x32_bf16 v[132:135], v[164:167], v[218:221], v[132:135]
	v_mfma_f32_16x16x32_bf16 v[128:131], v[184:187], v[218:221], v[128:131]
	v_mfma_f32_16x16x32_bf16 v[116:119], v[164:167], v[226:229], v[116:119]
	v_mfma_f32_16x16x32_bf16 v[112:115], v[184:187], v[226:229], v[112:115]
	v_mfma_f32_16x16x32_bf16 v[100:103], v[164:167], v[234:237], v[100:103]
	v_mfma_f32_16x16x32_bf16 v[96:99], v[184:187], v[234:237], v[96:99]
	v_mfma_f32_16x16x32_bf16 v[84:87], v[164:167], v[242:245], v[84:87]
	v_mfma_f32_16x16x32_bf16 v[80:83], v[184:187], v[242:245], v[80:83]
	s_setprio 0
	s_setprio 1
	v_mfma_f32_16x16x32_bf16 v[124:127], v[188:191], v[214:217], v[124:127]
	v_mfma_f32_16x16x32_bf16 v[120:123], v[196:199], v[214:217], v[120:123]
	v_mfma_f32_16x16x32_bf16 v[108:111], v[188:191], v[222:225], v[108:111]
	v_mfma_f32_16x16x32_bf16 v[104:107], v[196:199], v[222:225], v[104:107]
	v_mfma_f32_16x16x32_bf16 v[92:95], v[188:191], v[230:233], v[92:95]
	v_mfma_f32_16x16x32_bf16 v[88:91], v[196:199], v[230:233], v[88:91]
	v_mfma_f32_16x16x32_bf16 v[76:79], v[188:191], v[238:241], v[76:79]
	v_mfma_f32_16x16x32_bf16 v[72:75], v[196:199], v[238:241], v[72:75]
	v_mfma_f32_16x16x32_bf16 v[124:127], v[192:195], v[218:221], v[124:127]
	v_mfma_f32_16x16x32_bf16 v[120:123], v[200:203], v[218:221], v[120:123]
	v_mfma_f32_16x16x32_bf16 v[108:111], v[192:195], v[226:229], v[108:111]
	v_mfma_f32_16x16x32_bf16 v[104:107], v[200:203], v[226:229], v[104:107]
	v_mfma_f32_16x16x32_bf16 v[92:95], v[192:195], v[234:237], v[92:95]
	v_mfma_f32_16x16x32_bf16 v[88:91], v[200:203], v[234:237], v[88:91]
	v_mfma_f32_16x16x32_bf16 v[76:79], v[192:195], v[242:245], v[76:79]
	v_mfma_f32_16x16x32_bf16 v[72:75], v[200:203], v[242:245], v[72:75]
	s_setprio 0
	s_barrier
	s_add_i32 s42, s45, s53
	s_mov_b32 m0, s42
	ds_read_b128 v[214:217], v173 offset:49152
	ds_read_b128 v[218:221], v173 offset:50176
	ds_read_b128 v[222:225], v173 offset:51200
	ds_read_b128 v[226:229], v173 offset:52224
	ds_read_b128 v[230:233], v173 offset:53248
	ds_read_b128 v[234:237], v173 offset:54272
	ds_read_b128 v[238:241], v173 offset:55296
	ds_read_b128 v[242:245], v173 offset:56320
	global_load_lds_dwordx4 v136, s[98:99]
	s_add_i32 m0, s42, 0x2000
	s_add_u32 s38, s38, 0x80080
	s_addc_u32 s39, s39, 0
	s_add_i32 s42, s47, s53
	global_load_lds_dwordx4 v140, s[98:99]
	s_mov_b32 m0, s42
	s_nop 0
	global_load_lds_dwordx4 v136, s[38:39]
	s_add_i32 m0, s42, 0x2000
	s_nop 0
	global_load_lds_dwordx4 v140, s[38:39]
	s_mov_b32 m0, s61
	s_nop 0
	global_load_lds_dwordx4 v14, s[100:101]
	s_mov_b32 m0, s64
	s_nop 0
	global_load_lds_dwordx4 v138, s[100:101]
	s_waitcnt vmcnt(8)
	s_waitcnt lgkmcnt(0)
	s_barrier
	s_setprio 1
	s_waitcnt lgkmcnt(0)
	v_mfma_f32_16x16x32_bf16 v[68:71], v[160:163], v[214:217], v[68:71]
	v_mfma_f32_16x16x32_bf16 v[64:67], v[174:177], v[214:217], v[64:67]
	v_mfma_f32_16x16x32_bf16 v[52:55], v[160:163], v[222:225], v[52:55]
	v_mfma_f32_16x16x32_bf16 v[48:51], v[174:177], v[222:225], v[48:51]
	v_mfma_f32_16x16x32_bf16 v[36:39], v[160:163], v[230:233], v[36:39]
	v_mfma_f32_16x16x32_bf16 v[30:33], v[174:177], v[230:233], v[30:33]
	v_mfma_f32_16x16x32_bf16 v[18:21], v[160:163], v[238:241], v[18:21]
	v_mfma_f32_16x16x32_bf16 v[10:13], v[174:177], v[238:241], v[10:13]
	v_mfma_f32_16x16x32_bf16 v[68:71], v[164:167], v[218:221], v[68:71]
	v_mfma_f32_16x16x32_bf16 v[64:67], v[184:187], v[218:221], v[64:67]
	v_mfma_f32_16x16x32_bf16 v[52:55], v[164:167], v[226:229], v[52:55]
	v_mfma_f32_16x16x32_bf16 v[48:51], v[184:187], v[226:229], v[48:51]
	v_mfma_f32_16x16x32_bf16 v[36:39], v[164:167], v[234:237], v[36:39]
	v_mfma_f32_16x16x32_bf16 v[30:33], v[184:187], v[234:237], v[30:33]
	v_mfma_f32_16x16x32_bf16 v[18:21], v[164:167], v[242:245], v[18:21]
	v_mfma_f32_16x16x32_bf16 v[10:13], v[184:187], v[242:245], v[10:13]
	s_setprio 0
	s_setprio 1
	v_mfma_f32_16x16x32_bf16 v[60:63], v[188:191], v[214:217], v[60:63]
	v_mfma_f32_16x16x32_bf16 v[56:59], v[196:199], v[214:217], v[56:59]
	v_mfma_f32_16x16x32_bf16 v[44:47], v[188:191], v[222:225], v[44:47]
	v_mfma_f32_16x16x32_bf16 v[40:43], v[196:199], v[222:225], v[40:43]
	v_mfma_f32_16x16x32_bf16 v[26:29], v[188:191], v[230:233], v[26:29]
	v_mfma_f32_16x16x32_bf16 v[22:25], v[196:199], v[230:233], v[22:25]
	v_mfma_f32_16x16x32_bf16 v[6:9], v[188:191], v[238:241], v[6:9]
	v_mfma_f32_16x16x32_bf16 v[2:5], v[196:199], v[238:241], v[2:5]
	v_mfma_f32_16x16x32_bf16 v[60:63], v[192:195], v[218:221], v[60:63]
	v_mfma_f32_16x16x32_bf16 v[56:59], v[200:203], v[218:221], v[56:59]
	v_mfma_f32_16x16x32_bf16 v[44:47], v[192:195], v[226:229], v[44:47]
	v_mfma_f32_16x16x32_bf16 v[40:43], v[200:203], v[226:229], v[40:43]
	v_mfma_f32_16x16x32_bf16 v[26:29], v[192:195], v[234:237], v[26:29]
	v_mfma_f32_16x16x32_bf16 v[22:25], v[200:203], v[234:237], v[22:25]
	v_mfma_f32_16x16x32_bf16 v[6:9], v[192:195], v[242:245], v[6:9]
	v_mfma_f32_16x16x32_bf16 v[2:5], v[200:203], v[242:245], v[2:5]
	s_setprio 0
	s_barrier
	s_add_i32 s27, s27, 2
	s_add_u32 s36, s36, 0x100
	s_addc_u32 s37, s37, 0
	s_add_u32 s25, s25, 0x100
	s_addc_u32 s26, s26, 0
	s_cmp_gt_u32 s27, 29
	s_cbranch_scc0 .LBB0_306
	s_and_b64 vcc, exec, s[28:29]
	s_cbranch_vccz .LBB0_309
	s_barrier

.LBB0_1124:
	s_add_i32 vcc_lo, s44, 2
	s_add_u32 s38, s8, 0x100
	s_addc_u32 s39, s9, 0
	s_add_i32 s72, 0, 0x10000
	s_cmp_eq_u32 s29, s44
	s_cselect_b32 s47, s35, s39
	s_cselect_b32 s46, s34, s38
	v_add_u32_e32 v34, s72, v183
	s_cselect_b32 s45, s49, s71
	s_cselect_b32 s44, s48, s70
	s_add_i32 s73, 0, 0x14000
	ds_read_b128 v[42:45], v34
	ds_read_b128 v[46:49], v34 offset:1024
	ds_read_b128 v[74:77], v34 offset:2048
	ds_read_b128 v[78:81], v34 offset:3072
	v_add_u32_e32 v34, s73, v183
	ds_read_b128 v[106:109], v34
	ds_read_b128 v[110:113], v34 offset:1024
	ds_read_b128 v[138:141], v34 offset:2048
	ds_read_b128 v[142:145], v34 offset:3072
	s_add_i32 m0, s25, 0xc000
	ds_read_b128 v[170:173], v205
	ds_read_b128 v[174:177], v205 offset:1024
	ds_read_b128 v[196:199], v205 offset:2048
	ds_read_b128 v[200:203], v205 offset:3072
	ds_read_b128 v[214:217], v205 offset:4096
	ds_read_b128 v[218:221], v205 offset:5120
	ds_read_b128 v[222:225], v205 offset:6144
	ds_read_b128 v[226:229], v205 offset:7168
	global_load_lds_dwordx4 v192, s[8:9]
	s_add_i32 m0, s25, 0xe000
	s_nop 0
	global_load_lds_dwordx4 v194, s[8:9]
	s_waitcnt vmcnt(8)
	s_waitcnt lgkmcnt(0)
	s_barrier
	s_setprio 1
	s_waitcnt lgkmcnt(0)
	v_mfma_f32_16x16x32_bf16 v[62:65], v[42:45], v[170:173], v[62:65]
	v_mfma_f32_16x16x32_bf16 v[58:61], v[74:77], v[170:173], v[58:61]
	v_mfma_f32_16x16x32_bf16 v[94:97], v[42:45], v[196:199], v[94:97]
	v_mfma_f32_16x16x32_bf16 v[90:93], v[74:77], v[196:199], v[90:93]
	v_mfma_f32_16x16x32_bf16 v[118:121], v[42:45], v[214:217], v[118:121]
	v_mfma_f32_16x16x32_bf16 v[114:117], v[74:77], v[214:217], v[114:117]
	v_mfma_f32_16x16x32_bf16 v[134:137], v[42:45], v[222:225], v[134:137]
	v_mfma_f32_16x16x32_bf16 v[130:133], v[74:77], v[222:225], v[130:133]
	v_mfma_f32_16x16x32_bf16 v[62:65], v[46:49], v[174:177], v[62:65]
	v_mfma_f32_16x16x32_bf16 v[58:61], v[78:81], v[174:177], v[58:61]
	v_mfma_f32_16x16x32_bf16 v[94:97], v[46:49], v[200:203], v[94:97]
	v_mfma_f32_16x16x32_bf16 v[90:93], v[78:81], v[200:203], v[90:93]
	v_mfma_f32_16x16x32_bf16 v[118:121], v[46:49], v[218:221], v[118:121]
	v_mfma_f32_16x16x32_bf16 v[114:117], v[78:81], v[218:221], v[114:117]
	v_mfma_f32_16x16x32_bf16 v[134:137], v[46:49], v[226:229], v[134:137]
	v_mfma_f32_16x16x32_bf16 v[130:133], v[78:81], v[226:229], v[130:133]
	s_setprio 0
	s_setprio 1
	v_mfma_f32_16x16x32_bf16 v[166:169], v[106:109], v[170:173], v[166:169]
	v_mfma_f32_16x16x32_bf16 v[162:165], v[138:141], v[170:173], v[162:165]
	v_mfma_f32_16x16x32_bf16 v[158:161], v[106:109], v[196:199], v[158:161]
	v_mfma_f32_16x16x32_bf16 v[154:157], v[138:141], v[196:199], v[154:157]
	v_mfma_f32_16x16x32_bf16 v[150:153], v[106:109], v[214:217], v[150:153]
	v_mfma_f32_16x16x32_bf16 v[146:149], v[138:141], v[214:217], v[146:149]
	v_mfma_f32_16x16x32_bf16 v[126:129], v[106:109], v[222:225], v[126:129]
	v_mfma_f32_16x16x32_bf16 v[122:125], v[138:141], v[222:225], v[122:125]
	v_mfma_f32_16x16x32_bf16 v[166:169], v[110:113], v[174:177], v[166:169]
	v_mfma_f32_16x16x32_bf16 v[162:165], v[142:145], v[174:177], v[162:165]
	v_mfma_f32_16x16x32_bf16 v[158:161], v[110:113], v[200:203], v[158:161]
	v_mfma_f32_16x16x32_bf16 v[154:157], v[142:145], v[200:203], v[154:157]
	v_mfma_f32_16x16x32_bf16 v[150:153], v[110:113], v[218:221], v[150:153]
	v_mfma_f32_16x16x32_bf16 v[146:149], v[142:145], v[218:221], v[146:149]
	v_mfma_f32_16x16x32_bf16 v[126:129], v[110:113], v[226:229], v[126:129]
	v_mfma_f32_16x16x32_bf16 v[122:125], v[142:145], v[226:229], v[122:125]
	s_setprio 0
	s_barrier
	s_add_u32 s98, s44, s22
	s_addc_u32 s99, s45, s23
	s_add_u32 s100, s46, s22
	s_addc_u32 s101, s47, s23
	s_add_i32 s8, s72, s20
	s_mov_b32 m0, s8
	ds_read_b128 v[170:173], v205 offset:16384
	ds_read_b128 v[174:177], v205 offset:17408
	ds_read_b128 v[196:199], v205 offset:18432
	ds_read_b128 v[200:203], v205 offset:19456
	ds_read_b128 v[214:217], v205 offset:20480
	ds_read_b128 v[218:221], v205 offset:21504
	ds_read_b128 v[222:225], v205 offset:22528
	ds_read_b128 v[226:229], v205 offset:23552
	global_load_lds_dwordx4 v184, s[44:45]
	s_add_i32 m0, s8, 0x2000
	s_add_u32 s8, s44, 0xc0000
	s_addc_u32 s9, s45, 0
	s_add_i32 s72, s73, s20
	global_load_lds_dwordx4 v188, s[44:45]
	s_mov_b32 m0, s72
	global_load_lds_dwordx4 v184, s[8:9]
	s_add_i32 m0, s72, 0x2000
	global_load_lds_dwordx4 v188, s[8:9]
	s_mov_b32 m0, s25
	s_nop 0
	global_load_lds_dwordx4 v14, s[46:47]
	s_mov_b32 m0, s26
	s_nop 0
	global_load_lds_dwordx4 v186, s[46:47]
	s_waitcnt vmcnt(8)
	s_waitcnt lgkmcnt(0)
	s_barrier
	s_setprio 1
	s_waitcnt lgkmcnt(0)
	v_mfma_f32_16x16x32_bf16 v[102:105], v[42:45], v[170:173], v[102:105]
	v_mfma_f32_16x16x32_bf16 v[98:101], v[74:77], v[170:173], v[98:101]
	v_mfma_f32_16x16x32_bf16 v[70:73], v[42:45], v[196:199], v[70:73]
	v_mfma_f32_16x16x32_bf16 v[66:69], v[74:77], v[196:199], v[66:69]
	v_mfma_f32_16x16x32_bf16 v[36:39], v[42:45], v[214:217], v[38:41]
	v_mfma_f32_16x16x32_bf16 v[30:33], v[74:77], v[214:217], v[30:33]
	v_mfma_f32_16x16x32_bf16 v[18:21], v[42:45], v[222:225], v[18:21]
	v_mfma_f32_16x16x32_bf16 v[10:13], v[74:77], v[222:225], v[10:13]
	v_mfma_f32_16x16x32_bf16 v[102:105], v[46:49], v[174:177], v[102:105]
	v_mfma_f32_16x16x32_bf16 v[98:101], v[78:81], v[174:177], v[98:101]
	v_mfma_f32_16x16x32_bf16 v[70:73], v[46:49], v[200:203], v[70:73]
	v_mfma_f32_16x16x32_bf16 v[66:69], v[78:81], v[200:203], v[66:69]
	v_mfma_f32_16x16x32_bf16 v[36:39], v[46:49], v[218:221], v[36:39]
	v_mfma_f32_16x16x32_bf16 v[30:33], v[78:81], v[218:221], v[30:33]
	v_mfma_f32_16x16x32_bf16 v[18:21], v[46:49], v[226:229], v[18:21]
	v_mfma_f32_16x16x32_bf16 v[10:13], v[78:81], v[226:229], v[10:13]
	s_setprio 0
	s_setprio 1
	v_mfma_f32_16x16x32_bf16 v[54:57], v[106:109], v[196:199], v[54:57]
	v_mfma_f32_16x16x32_bf16 v[50:53], v[138:141], v[196:199], v[50:53]
	v_mfma_f32_16x16x32_bf16 v[26:29], v[106:109], v[214:217], v[26:29]
	v_mfma_f32_16x16x32_bf16 v[22:25], v[138:141], v[214:217], v[22:25]
	v_mfma_f32_16x16x32_bf16 v[6:9], v[106:109], v[222:225], v[6:9]
	v_mfma_f32_16x16x32_bf16 v[2:5], v[138:141], v[222:225], v[2:5]
	v_mfma_f32_16x16x32_bf16 v[40:43], v[106:109], v[170:173], v[86:89]
	v_mfma_f32_16x16x32_bf16 v[46:49], v[138:141], v[170:173], v[82:85]
	v_mfma_f32_16x16x32_bf16 v[54:57], v[110:113], v[200:203], v[54:57]
	v_mfma_f32_16x16x32_bf16 v[50:53], v[142:145], v[200:203], v[50:53]
	v_mfma_f32_16x16x32_bf16 v[26:29], v[110:113], v[218:221], v[26:29]
	v_mfma_f32_16x16x32_bf16 v[22:25], v[142:145], v[218:221], v[22:25]
	v_mfma_f32_16x16x32_bf16 v[6:9], v[110:113], v[226:229], v[6:9]
	v_mfma_f32_16x16x32_bf16 v[2:5], v[142:145], v[226:229], v[2:5]
	v_mfma_f32_16x16x32_bf16 v[42:45], v[110:113], v[174:177], v[40:43]
	v_mfma_f32_16x16x32_bf16 v[46:49], v[142:145], v[174:177], v[46:49]
	s_setprio 0
	s_barrier
	s_add_i32 s72, 0, 0x18000
	v_add_u32_e32 v34, s72, v183
	s_add_i32 s73, 0, 0x1c000
	ds_read_b128 v[74:77], v34
	ds_read_b128 v[78:81], v34 offset:1024
	ds_read_b128 v[82:85], v34 offset:2048
	ds_read_b128 v[86:89], v34 offset:3072
	v_add_u32_e32 v34, s73, v183
	ds_read_b128 v[106:109], v34
	ds_read_b128 v[110:113], v34 offset:1024
	ds_read_b128 v[138:141], v34 offset:2048
	ds_read_b128 v[142:145], v34 offset:3072
	s_add_u32 s8, s46, 0xc0000
	s_addc_u32 s9, s47, 0
	s_mov_b32 m0, s27
	ds_read_b128 v[170:173], v205 offset:32768
	ds_read_b128 v[174:177], v205 offset:33792
	ds_read_b128 v[196:199], v205 offset:34816
	ds_read_b128 v[200:203], v205 offset:35840
	ds_read_b128 v[214:217], v205 offset:36864
	ds_read_b128 v[218:221], v205 offset:37888
	ds_read_b128 v[222:225], v205 offset:38912
	ds_read_b128 v[226:229], v205 offset:39936
	global_load_lds_dwordx4 v14, s[8:9]
	s_mov_b32 m0, s31
	s_nop 0
	global_load_lds_dwordx4 v186, s[8:9]
	s_waitcnt vmcnt(8)
	s_waitcnt lgkmcnt(0)
	s_barrier
	s_setprio 1
	s_waitcnt lgkmcnt(0)
	v_mfma_f32_16x16x32_bf16 v[62:65], v[74:77], v[170:173], v[62:65]
	v_mfma_f32_16x16x32_bf16 v[58:61], v[82:85], v[170:173], v[58:61]
	v_mfma_f32_16x16x32_bf16 v[94:97], v[74:77], v[196:199], v[94:97]
	v_mfma_f32_16x16x32_bf16 v[90:93], v[82:85], v[196:199], v[90:93]
	v_mfma_f32_16x16x32_bf16 v[118:121], v[74:77], v[214:217], v[118:121]
	v_mfma_f32_16x16x32_bf16 v[114:117], v[82:85], v[214:217], v[114:117]
	v_mfma_f32_16x16x32_bf16 v[134:137], v[74:77], v[222:225], v[134:137]
	v_mfma_f32_16x16x32_bf16 v[130:133], v[82:85], v[222:225], v[130:133]
	v_mfma_f32_16x16x32_bf16 v[62:65], v[78:81], v[174:177], v[62:65]
	v_mfma_f32_16x16x32_bf16 v[58:61], v[86:89], v[174:177], v[58:61]
	v_mfma_f32_16x16x32_bf16 v[94:97], v[78:81], v[200:203], v[94:97]
	v_mfma_f32_16x16x32_bf16 v[90:93], v[86:89], v[200:203], v[90:93]
	v_mfma_f32_16x16x32_bf16 v[118:121], v[78:81], v[218:221], v[118:121]
	v_mfma_f32_16x16x32_bf16 v[114:117], v[86:89], v[218:221], v[114:117]
	v_mfma_f32_16x16x32_bf16 v[134:137], v[78:81], v[226:229], v[134:137]
	v_mfma_f32_16x16x32_bf16 v[130:133], v[86:89], v[226:229], v[130:133]
	s_setprio 0
	s_setprio 1
	v_mfma_f32_16x16x32_bf16 v[166:169], v[106:109], v[170:173], v[166:169]
	v_mfma_f32_16x16x32_bf16 v[162:165], v[138:141], v[170:173], v[162:165]
	v_mfma_f32_16x16x32_bf16 v[158:161], v[106:109], v[196:199], v[158:161]
	v_mfma_f32_16x16x32_bf16 v[154:157], v[138:141], v[196:199], v[154:157]
	v_mfma_f32_16x16x32_bf16 v[150:153], v[106:109], v[214:217], v[150:153]
	v_mfma_f32_16x16x32_bf16 v[146:149], v[138:141], v[214:217], v[146:149]
	v_mfma_f32_16x16x32_bf16 v[126:129], v[106:109], v[222:225], v[126:129]
	v_mfma_f32_16x16x32_bf16 v[122:125], v[138:141], v[222:225], v[122:125]
	v_mfma_f32_16x16x32_bf16 v[166:169], v[110:113], v[174:177], v[166:169]
	v_mfma_f32_16x16x32_bf16 v[162:165], v[142:145], v[174:177], v[162:165]
	v_mfma_f32_16x16x32_bf16 v[158:161], v[110:113], v[200:203], v[158:161]
	v_mfma_f32_16x16x32_bf16 v[154:157], v[142:145], v[200:203], v[154:157]
	v_mfma_f32_16x16x32_bf16 v[150:153], v[110:113], v[218:221], v[150:153]
	v_mfma_f32_16x16x32_bf16 v[146:149], v[142:145], v[218:221], v[146:149]
	v_mfma_f32_16x16x32_bf16 v[126:129], v[110:113], v[226:229], v[126:129]
	v_mfma_f32_16x16x32_bf16 v[122:125], v[142:145], v[226:229], v[122:125]
	s_setprio 0
	s_barrier
	s_add_i32 s8, s72, s20
	s_mov_b32 m0, s8
	ds_read_b128 v[170:173], v205 offset:49152
	ds_read_b128 v[174:177], v205 offset:50176
	ds_read_b128 v[196:199], v205 offset:51200
	ds_read_b128 v[200:203], v205 offset:52224
	ds_read_b128 v[214:217], v205 offset:53248
	ds_read_b128 v[218:221], v205 offset:54272
	ds_read_b128 v[222:225], v205 offset:55296
	ds_read_b128 v[226:229], v205 offset:56320
	global_load_lds_dwordx4 v184, s[98:99]
	s_add_i32 m0, s8, 0x2000
	s_add_u32 s8, s44, 0xc0080
	s_addc_u32 s9, s45, 0
	s_add_i32 s44, s73, s20
	global_load_lds_dwordx4 v188, s[98:99]
	s_mov_b32 m0, s44
	s_nop 0
	global_load_lds_dwordx4 v184, s[8:9]
	s_add_i32 m0, s44, 0x2000
	s_nop 0
	global_load_lds_dwordx4 v188, s[8:9]
	s_mov_b32 m0, s52
	s_nop 0
	global_load_lds_dwordx4 v14, s[100:101]
	s_mov_b32 m0, s53
	s_nop 0
	global_load_lds_dwordx4 v186, s[100:101]
	s_waitcnt vmcnt(8)
	s_waitcnt lgkmcnt(0)
	s_barrier
	s_setprio 1
	s_waitcnt lgkmcnt(0)
	v_mfma_f32_16x16x32_bf16 v[102:105], v[74:77], v[170:173], v[102:105]
	v_mfma_f32_16x16x32_bf16 v[98:101], v[82:85], v[170:173], v[98:101]
	v_mfma_f32_16x16x32_bf16 v[70:73], v[74:77], v[196:199], v[70:73]
	v_mfma_f32_16x16x32_bf16 v[66:69], v[82:85], v[196:199], v[66:69]
	v_mfma_f32_16x16x32_bf16 v[36:39], v[74:77], v[214:217], v[36:39]
	v_mfma_f32_16x16x32_bf16 v[30:33], v[82:85], v[214:217], v[30:33]
	v_mfma_f32_16x16x32_bf16 v[18:21], v[74:77], v[222:225], v[18:21]
	v_mfma_f32_16x16x32_bf16 v[10:13], v[82:85], v[222:225], v[10:13]
	v_mfma_f32_16x16x32_bf16 v[102:105], v[78:81], v[174:177], v[102:105]
	v_mfma_f32_16x16x32_bf16 v[98:101], v[86:89], v[174:177], v[98:101]
	v_mfma_f32_16x16x32_bf16 v[70:73], v[78:81], v[200:203], v[70:73]
	v_mfma_f32_16x16x32_bf16 v[66:69], v[86:89], v[200:203], v[66:69]
	v_mfma_f32_16x16x32_bf16 v[38:41], v[78:81], v[218:221], v[36:39]
	v_mfma_f32_16x16x32_bf16 v[30:33], v[86:89], v[218:221], v[30:33]
	v_mfma_f32_16x16x32_bf16 v[18:21], v[78:81], v[226:229], v[18:21]
	v_mfma_f32_16x16x32_bf16 v[10:13], v[86:89], v[226:229], v[10:13]
	s_setprio 0
	s_setprio 1
	v_mfma_f32_16x16x32_bf16 v[42:45], v[106:109], v[170:173], v[42:45]
	v_mfma_f32_16x16x32_bf16 v[86:89], v[110:113], v[174:177], v[42:45]
	v_mfma_f32_16x16x32_bf16 v[42:45], v[138:141], v[170:173], v[46:49]
	v_mfma_f32_16x16x32_bf16 v[82:85], v[142:145], v[174:177], v[42:45]
	v_mfma_f32_16x16x32_bf16 v[42:45], v[106:109], v[196:199], v[54:57]
	v_mfma_f32_16x16x32_bf16 v[54:57], v[110:113], v[200:203], v[42:45]
	v_mfma_f32_16x16x32_bf16 v[42:45], v[138:141], v[196:199], v[50:53]
	v_mfma_f32_16x16x32_bf16 v[26:29], v[106:109], v[214:217], v[26:29]
	v_mfma_f32_16x16x32_bf16 v[22:25], v[138:141], v[214:217], v[22:25]
	v_mfma_f32_16x16x32_bf16 v[6:9], v[106:109], v[222:225], v[6:9]
	v_mfma_f32_16x16x32_bf16 v[2:5], v[138:141], v[222:225], v[2:5]
	v_mfma_f32_16x16x32_bf16 v[50:53], v[142:145], v[200:203], v[42:45]
	v_mfma_f32_16x16x32_bf16 v[26:29], v[110:113], v[218:221], v[26:29]
	v_mfma_f32_16x16x32_bf16 v[22:25], v[142:145], v[218:221], v[22:25]
	v_mfma_f32_16x16x32_bf16 v[6:9], v[110:113], v[226:229], v[6:9]
	v_mfma_f32_16x16x32_bf16 v[2:5], v[142:145], v[226:229], v[2:5]
	s_setprio 0
	s_barrier
	s_add_u32 s70, s70, 0x100
	s_addc_u32 s71, s71, 0
	s_cmp_ge_i32 vcc_lo, s51
	s_mov_b64 s[8:9], s[38:39]
	s_mov_b32 s44, vcc_lo
	s_cbranch_scc0 .LBB0_1124
	s_and_b64 vcc, exec, s[12:13]
	s_cbranch_vccz .LBB0_1127
	s_barrier

.LBB0_1508:
	s_add_i32 s39, s35, 2
	s_add_u32 s50, s48, 0xfff80080
	s_addc_u32 s51, s49, -1
	s_add_i32 s72, 0, 0x10000
	s_cmp_eq_u32 s9, s35
	s_cselect_b32 s53, s37, s51
	s_cselect_b32 s52, s36, s50
	s_cselect_b32 s51, s45, s29
	s_cselect_b32 s50, s44, s13
	s_add_i32 s35, 0, 0x14000
	v_add_u32_e32 v160, s72, v152
	v_add_u32_e32 v176, s35, v152
	ds_read_b128 v[136:139], v160
	ds_read_b128 v[148:151], v160 offset:1024
	ds_read_b128 v[156:159], v160 offset:2048
	ds_read_b128 v[160:163], v160 offset:3072
	ds_read_b128 v[164:167], v176
	ds_read_b128 v[168:171], v176 offset:1024
	ds_read_b128 v[172:175], v176 offset:2048
	ds_read_b128 v[184:187], v176 offset:3072
	s_add_i32 m0, s25, 0xc000
	ds_read_b128 v[188:191], v155
	ds_read_b128 v[192:195], v155 offset:1024
	ds_read_b128 v[196:199], v155 offset:2048
	ds_read_b128 v[200:203], v155 offset:3072
	ds_read_b128 v[214:217], v155 offset:4096
	ds_read_b128 v[218:221], v155 offset:5120
	ds_read_b128 v[222:225], v155 offset:6144
	ds_read_b128 v[226:229], v155 offset:7168
	global_load_lds_dwordx4 v144, s[48:49]
	s_add_i32 m0, s25, 0xe000
	s_nop 0
	global_load_lds_dwordx4 v146, s[48:49]
	s_waitcnt vmcnt(8)
	s_waitcnt lgkmcnt(0)
	s_barrier
	s_setprio 1
	s_waitcnt lgkmcnt(0)
	v_mfma_f32_16x16x32_bf16 v[132:135], v[136:139], v[188:191], v[132:135]
	v_mfma_f32_16x16x32_bf16 v[128:131], v[156:159], v[188:191], v[128:131]
	v_mfma_f32_16x16x32_bf16 v[116:119], v[136:139], v[196:199], v[116:119]
	v_mfma_f32_16x16x32_bf16 v[112:115], v[156:159], v[196:199], v[112:115]
	v_mfma_f32_16x16x32_bf16 v[100:103], v[136:139], v[214:217], v[100:103]
	v_mfma_f32_16x16x32_bf16 v[96:99], v[156:159], v[214:217], v[96:99]
	v_mfma_f32_16x16x32_bf16 v[84:87], v[136:139], v[222:225], v[84:87]
	v_mfma_f32_16x16x32_bf16 v[80:83], v[156:159], v[222:225], v[80:83]
	v_mfma_f32_16x16x32_bf16 v[132:135], v[148:151], v[192:195], v[132:135]
	v_mfma_f32_16x16x32_bf16 v[128:131], v[160:163], v[192:195], v[128:131]
	v_mfma_f32_16x16x32_bf16 v[116:119], v[148:151], v[200:203], v[116:119]
	v_mfma_f32_16x16x32_bf16 v[112:115], v[160:163], v[200:203], v[112:115]
	v_mfma_f32_16x16x32_bf16 v[100:103], v[148:151], v[218:221], v[100:103]
	v_mfma_f32_16x16x32_bf16 v[96:99], v[160:163], v[218:221], v[96:99]
	v_mfma_f32_16x16x32_bf16 v[84:87], v[148:151], v[226:229], v[84:87]
	v_mfma_f32_16x16x32_bf16 v[80:83], v[160:163], v[226:229], v[80:83]
	s_setprio 0
	s_setprio 1
	v_mfma_f32_16x16x32_bf16 v[124:127], v[164:167], v[188:191], v[124:127]
	v_mfma_f32_16x16x32_bf16 v[120:123], v[172:175], v[188:191], v[120:123]
	v_mfma_f32_16x16x32_bf16 v[108:111], v[164:167], v[196:199], v[108:111]
	v_mfma_f32_16x16x32_bf16 v[104:107], v[172:175], v[196:199], v[104:107]
	v_mfma_f32_16x16x32_bf16 v[92:95], v[164:167], v[214:217], v[92:95]
	v_mfma_f32_16x16x32_bf16 v[88:91], v[172:175], v[214:217], v[88:91]
	v_mfma_f32_16x16x32_bf16 v[76:79], v[164:167], v[222:225], v[76:79]
	v_mfma_f32_16x16x32_bf16 v[72:75], v[172:175], v[222:225], v[72:75]
	v_mfma_f32_16x16x32_bf16 v[124:127], v[168:171], v[192:195], v[124:127]
	v_mfma_f32_16x16x32_bf16 v[120:123], v[184:187], v[192:195], v[120:123]
	v_mfma_f32_16x16x32_bf16 v[108:111], v[168:171], v[200:203], v[108:111]
	v_mfma_f32_16x16x32_bf16 v[104:107], v[184:187], v[200:203], v[104:107]
	v_mfma_f32_16x16x32_bf16 v[92:95], v[168:171], v[218:221], v[92:95]
	v_mfma_f32_16x16x32_bf16 v[88:91], v[184:187], v[218:221], v[88:91]
	v_mfma_f32_16x16x32_bf16 v[76:79], v[168:171], v[226:229], v[76:79]
	v_mfma_f32_16x16x32_bf16 v[72:75], v[184:187], v[226:229], v[72:75]
	s_setprio 0
	s_barrier
	s_add_u32 s98, s50, s22
	s_addc_u32 s99, s51, s23
	s_add_u32 s100, s52, s22
	s_addc_u32 s101, s53, s23
	s_add_i32 s72, s72, s20
	s_mov_b32 m0, s72
	ds_read_b128 v[188:191], v155 offset:16384
	ds_read_b128 v[192:195], v155 offset:17408
	ds_read_b128 v[196:199], v155 offset:18432
	ds_read_b128 v[200:203], v155 offset:19456
	ds_read_b128 v[214:217], v155 offset:20480
	ds_read_b128 v[218:221], v155 offset:21504
	ds_read_b128 v[222:225], v155 offset:22528
	ds_read_b128 v[226:229], v155 offset:23552
	global_load_lds_dwordx4 v34, s[50:51]
	s_add_i32 m0, s72, 0x2000
	s_add_u32 s72, s50, 0x80000
	s_addc_u32 s73, s51, 0
	s_add_i32 s35, s35, s20
	global_load_lds_dwordx4 v142, s[50:51]
	s_mov_b32 m0, s35
	global_load_lds_dwordx4 v34, s[72:73]
	s_add_i32 m0, s35, 0x2000
	s_nop 0
	global_load_lds_dwordx4 v142, s[72:73]
	s_mov_b32 m0, s25
	s_nop 0
	global_load_lds_dwordx4 v14, s[52:53]
	s_mov_b32 m0, s26
	s_nop 0
	global_load_lds_dwordx4 v140, s[52:53]
	s_waitcnt vmcnt(8)
	s_waitcnt lgkmcnt(0)
	s_barrier
	s_setprio 1
	s_waitcnt lgkmcnt(0)
	v_mfma_f32_16x16x32_bf16 v[68:71], v[136:139], v[188:191], v[68:71]
	v_mfma_f32_16x16x32_bf16 v[64:67], v[156:159], v[188:191], v[64:67]
	v_mfma_f32_16x16x32_bf16 v[52:55], v[136:139], v[196:199], v[52:55]
	v_mfma_f32_16x16x32_bf16 v[48:51], v[156:159], v[196:199], v[48:51]
	v_mfma_f32_16x16x32_bf16 v[36:39], v[136:139], v[214:217], v[36:39]
	v_mfma_f32_16x16x32_bf16 v[30:33], v[156:159], v[214:217], v[30:33]
	v_mfma_f32_16x16x32_bf16 v[18:21], v[136:139], v[222:225], v[18:21]
	v_mfma_f32_16x16x32_bf16 v[10:13], v[156:159], v[222:225], v[10:13]
	v_mfma_f32_16x16x32_bf16 v[68:71], v[148:151], v[192:195], v[68:71]
	v_mfma_f32_16x16x32_bf16 v[64:67], v[160:163], v[192:195], v[64:67]
	v_mfma_f32_16x16x32_bf16 v[52:55], v[148:151], v[200:203], v[52:55]
	v_mfma_f32_16x16x32_bf16 v[48:51], v[160:163], v[200:203], v[48:51]
	v_mfma_f32_16x16x32_bf16 v[36:39], v[148:151], v[218:221], v[36:39]
	v_mfma_f32_16x16x32_bf16 v[30:33], v[160:163], v[218:221], v[30:33]
	v_mfma_f32_16x16x32_bf16 v[18:21], v[148:151], v[226:229], v[18:21]
	v_mfma_f32_16x16x32_bf16 v[10:13], v[160:163], v[226:229], v[10:13]
	s_setprio 0
	s_setprio 1
	v_mfma_f32_16x16x32_bf16 v[60:63], v[164:167], v[188:191], v[60:63]
	v_mfma_f32_16x16x32_bf16 v[56:59], v[172:175], v[188:191], v[56:59]
	v_mfma_f32_16x16x32_bf16 v[44:47], v[164:167], v[196:199], v[44:47]
	v_mfma_f32_16x16x32_bf16 v[40:43], v[172:175], v[196:199], v[40:43]
	v_mfma_f32_16x16x32_bf16 v[26:29], v[164:167], v[214:217], v[26:29]
	v_mfma_f32_16x16x32_bf16 v[22:25], v[172:175], v[214:217], v[22:25]
	v_mfma_f32_16x16x32_bf16 v[6:9], v[164:167], v[222:225], v[6:9]
	v_mfma_f32_16x16x32_bf16 v[2:5], v[172:175], v[222:225], v[2:5]
	v_mfma_f32_16x16x32_bf16 v[60:63], v[168:171], v[192:195], v[60:63]
	v_mfma_f32_16x16x32_bf16 v[56:59], v[184:187], v[192:195], v[56:59]
	v_mfma_f32_16x16x32_bf16 v[44:47], v[168:171], v[200:203], v[44:47]
	v_mfma_f32_16x16x32_bf16 v[40:43], v[184:187], v[200:203], v[40:43]
	v_mfma_f32_16x16x32_bf16 v[26:29], v[168:171], v[218:221], v[26:29]
	v_mfma_f32_16x16x32_bf16 v[22:25], v[184:187], v[218:221], v[22:25]
	v_mfma_f32_16x16x32_bf16 v[6:9], v[168:171], v[226:229], v[6:9]
	v_mfma_f32_16x16x32_bf16 v[2:5], v[184:187], v[226:229], v[2:5]
	s_setprio 0
	s_barrier
	s_add_i32 s35, 0, 0x18000
	s_add_i32 s72, 0, 0x1c000
	v_add_u32_e32 v160, s35, v152
	v_add_u32_e32 v183, s72, v152
	ds_read_b128 v[136:139], v160
	ds_read_b128 v[148:151], v160 offset:1024
	ds_read_b128 v[156:159], v160 offset:2048
	ds_read_b128 v[160:163], v160 offset:3072
	ds_read_b128 v[164:167], v183
	ds_read_b128 v[168:171], v183 offset:1024
	ds_read_b128 v[172:175], v183 offset:2048
	ds_read_b128 v[184:187], v183 offset:3072
	s_add_u32 s52, s52, 0x80000
	s_addc_u32 s53, s53, 0
	s_mov_b32 m0, s27
	ds_read_b128 v[188:191], v155 offset:32768
	ds_read_b128 v[192:195], v155 offset:33792
	ds_read_b128 v[196:199], v155 offset:34816
	ds_read_b128 v[200:203], v155 offset:35840
	ds_read_b128 v[214:217], v155 offset:36864
	ds_read_b128 v[218:221], v155 offset:37888
	ds_read_b128 v[222:225], v155 offset:38912
	ds_read_b128 v[226:229], v155 offset:39936
	global_load_lds_dwordx4 v14, s[52:53]
	s_mov_b32 m0, s31
	s_nop 0
	global_load_lds_dwordx4 v140, s[52:53]
	s_waitcnt vmcnt(8)
	s_waitcnt lgkmcnt(0)
	s_barrier
	s_setprio 1
	s_waitcnt lgkmcnt(0)
	v_mfma_f32_16x16x32_bf16 v[132:135], v[136:139], v[188:191], v[132:135]
	v_mfma_f32_16x16x32_bf16 v[128:131], v[156:159], v[188:191], v[128:131]
	v_mfma_f32_16x16x32_bf16 v[116:119], v[136:139], v[196:199], v[116:119]
	v_mfma_f32_16x16x32_bf16 v[112:115], v[156:159], v[196:199], v[112:115]
	v_mfma_f32_16x16x32_bf16 v[100:103], v[136:139], v[214:217], v[100:103]
	v_mfma_f32_16x16x32_bf16 v[96:99], v[156:159], v[214:217], v[96:99]
	v_mfma_f32_16x16x32_bf16 v[84:87], v[136:139], v[222:225], v[84:87]
	v_mfma_f32_16x16x32_bf16 v[80:83], v[156:159], v[222:225], v[80:83]
	v_mfma_f32_16x16x32_bf16 v[132:135], v[148:151], v[192:195], v[132:135]
	v_mfma_f32_16x16x32_bf16 v[128:131], v[160:163], v[192:195], v[128:131]
	v_mfma_f32_16x16x32_bf16 v[116:119], v[148:151], v[200:203], v[116:119]
	v_mfma_f32_16x16x32_bf16 v[112:115], v[160:163], v[200:203], v[112:115]
	v_mfma_f32_16x16x32_bf16 v[100:103], v[148:151], v[218:221], v[100:103]
	v_mfma_f32_16x16x32_bf16 v[96:99], v[160:163], v[218:221], v[96:99]
	v_mfma_f32_16x16x32_bf16 v[84:87], v[148:151], v[226:229], v[84:87]
	v_mfma_f32_16x16x32_bf16 v[80:83], v[160:163], v[226:229], v[80:83]
	s_setprio 0
	s_setprio 1
	v_mfma_f32_16x16x32_bf16 v[124:127], v[164:167], v[188:191], v[124:127]
	v_mfma_f32_16x16x32_bf16 v[120:123], v[172:175], v[188:191], v[120:123]
	v_mfma_f32_16x16x32_bf16 v[108:111], v[164:167], v[196:199], v[108:111]
	v_mfma_f32_16x16x32_bf16 v[104:107], v[172:175], v[196:199], v[104:107]
	v_mfma_f32_16x16x32_bf16 v[92:95], v[164:167], v[214:217], v[92:95]
	v_mfma_f32_16x16x32_bf16 v[88:91], v[172:175], v[214:217], v[88:91]
	v_mfma_f32_16x16x32_bf16 v[76:79], v[164:167], v[222:225], v[76:79]
	v_mfma_f32_16x16x32_bf16 v[72:75], v[172:175], v[222:225], v[72:75]
	v_mfma_f32_16x16x32_bf16 v[124:127], v[168:171], v[192:195], v[124:127]
	v_mfma_f32_16x16x32_bf16 v[120:123], v[184:187], v[192:195], v[120:123]
	v_mfma_f32_16x16x32_bf16 v[108:111], v[168:171], v[200:203], v[108:111]
	v_mfma_f32_16x16x32_bf16 v[104:107], v[184:187], v[200:203], v[104:107]
	v_mfma_f32_16x16x32_bf16 v[92:95], v[168:171], v[218:221], v[92:95]
	v_mfma_f32_16x16x32_bf16 v[88:91], v[184:187], v[218:221], v[88:91]
	v_mfma_f32_16x16x32_bf16 v[76:79], v[168:171], v[226:229], v[76:79]
	v_mfma_f32_16x16x32_bf16 v[72:75], v[184:187], v[226:229], v[72:75]
	s_setprio 0
	s_barrier
	s_add_i32 s35, s35, s20
	s_mov_b32 m0, s35
	ds_read_b128 v[188:191], v155 offset:49152
	ds_read_b128 v[192:195], v155 offset:50176
	ds_read_b128 v[196:199], v155 offset:51200
	ds_read_b128 v[200:203], v155 offset:52224
	ds_read_b128 v[214:217], v155 offset:53248
	ds_read_b128 v[218:221], v155 offset:54272
	ds_read_b128 v[222:225], v155 offset:55296
	ds_read_b128 v[226:229], v155 offset:56320
	global_load_lds_dwordx4 v34, s[98:99]
	s_add_i32 m0, s35, 0x2000
	s_add_u32 s50, s50, 0x80080
	s_addc_u32 s51, s51, 0
	s_add_i32 s35, s72, s20
	global_load_lds_dwordx4 v142, s[98:99]
	s_mov_b32 m0, s35
	s_nop 0
	global_load_lds_dwordx4 v34, s[50:51]
	s_add_i32 m0, s35, 0x2000
	s_nop 0
	global_load_lds_dwordx4 v142, s[50:51]
	s_mov_b32 m0, s60
	s_nop 0
	global_load_lds_dwordx4 v14, s[100:101]
	s_mov_b32 m0, s61
	s_nop 0
	global_load_lds_dwordx4 v140, s[100:101]
	s_waitcnt vmcnt(8)
	s_waitcnt lgkmcnt(0)
	s_barrier
	s_setprio 1
	s_waitcnt lgkmcnt(0)
	v_mfma_f32_16x16x32_bf16 v[68:71], v[136:139], v[188:191], v[68:71]
	v_mfma_f32_16x16x32_bf16 v[64:67], v[156:159], v[188:191], v[64:67]
	v_mfma_f32_16x16x32_bf16 v[52:55], v[136:139], v[196:199], v[52:55]
	v_mfma_f32_16x16x32_bf16 v[48:51], v[156:159], v[196:199], v[48:51]
	v_mfma_f32_16x16x32_bf16 v[36:39], v[136:139], v[214:217], v[36:39]
	v_mfma_f32_16x16x32_bf16 v[30:33], v[156:159], v[214:217], v[30:33]
	v_mfma_f32_16x16x32_bf16 v[18:21], v[136:139], v[222:225], v[18:21]
	v_mfma_f32_16x16x32_bf16 v[10:13], v[156:159], v[222:225], v[10:13]
	v_mfma_f32_16x16x32_bf16 v[68:71], v[148:151], v[192:195], v[68:71]
	v_mfma_f32_16x16x32_bf16 v[64:67], v[160:163], v[192:195], v[64:67]
	v_mfma_f32_16x16x32_bf16 v[52:55], v[148:151], v[200:203], v[52:55]
	v_mfma_f32_16x16x32_bf16 v[48:51], v[160:163], v[200:203], v[48:51]
	v_mfma_f32_16x16x32_bf16 v[36:39], v[148:151], v[218:221], v[36:39]
	v_mfma_f32_16x16x32_bf16 v[30:33], v[160:163], v[218:221], v[30:33]
	v_mfma_f32_16x16x32_bf16 v[18:21], v[148:151], v[226:229], v[18:21]
	v_mfma_f32_16x16x32_bf16 v[10:13], v[160:163], v[226:229], v[10:13]
	s_setprio 0
	s_setprio 1
	v_mfma_f32_16x16x32_bf16 v[60:63], v[164:167], v[188:191], v[60:63]
	v_mfma_f32_16x16x32_bf16 v[56:59], v[172:175], v[188:191], v[56:59]
	v_mfma_f32_16x16x32_bf16 v[44:47], v[164:167], v[196:199], v[44:47]
	v_mfma_f32_16x16x32_bf16 v[40:43], v[172:175], v[196:199], v[40:43]
	v_mfma_f32_16x16x32_bf16 v[26:29], v[164:167], v[214:217], v[26:29]
	v_mfma_f32_16x16x32_bf16 v[22:25], v[172:175], v[214:217], v[22:25]
	v_mfma_f32_16x16x32_bf16 v[6:9], v[164:167], v[222:225], v[6:9]
	v_mfma_f32_16x16x32_bf16 v[2:5], v[172:175], v[222:225], v[2:5]
	v_mfma_f32_16x16x32_bf16 v[60:63], v[168:171], v[192:195], v[60:63]
	v_mfma_f32_16x16x32_bf16 v[56:59], v[184:187], v[192:195], v[56:59]
	v_mfma_f32_16x16x32_bf16 v[44:47], v[168:171], v[200:203], v[44:47]
	v_mfma_f32_16x16x32_bf16 v[40:43], v[184:187], v[200:203], v[40:43]
	v_mfma_f32_16x16x32_bf16 v[26:29], v[168:171], v[218:221], v[26:29]
	v_mfma_f32_16x16x32_bf16 v[22:25], v[184:187], v[218:221], v[22:25]
	v_mfma_f32_16x16x32_bf16 v[6:9], v[168:171], v[226:229], v[6:9]
	v_mfma_f32_16x16x32_bf16 v[2:5], v[184:187], v[226:229], v[2:5]
	s_setprio 0
	s_barrier
	s_add_u32 s48, s48, 0x100
	s_addc_u32 s49, s49, 0
	s_add_u32 s13, s13, 0x100
	s_addc_u32 s29, s29, 0
	s_cmp_ge_i32 s39, s71
	s_mov_b32 s35, s39
	s_cbranch_scc0 .LBB0_1508
	s_and_b64 vcc, exec, s[10:11]
	s_cbranch_vccz .LBB0_1511

.LBB0_1664:
	s_add_u32 s44, s42, 0xfff80080
	s_addc_u32 s45, s43, -1
	s_add_i32 s64, 0, 0x10000
	s_cmp_eq_u32 s61, 28
	s_cselect_b32 s47, s29, s45
	s_cselect_b32 s46, s53, s44
	v_add_u32_e32 v151, s64, v141
	s_cselect_b32 s45, s13, s60
	s_cselect_b32 s44, s54, s55
	s_add_i32 s67, 0, 0x14000
	ds_read_b128 v[162:165], v151
	ds_read_b128 v[166:169], v151 offset:1024
	ds_read_b128 v[170:173], v151 offset:2048
	ds_read_b128 v[174:177], v151 offset:3072
	v_add_u32_e32 v151, s67, v141
	ds_read_b128 v[184:187], v151
	ds_read_b128 v[188:191], v151 offset:1024
	ds_read_b128 v[192:195], v151 offset:2048
	ds_read_b128 v[196:199], v151 offset:3072
	s_add_i32 m0, s25, 0xc000
	ds_read_b128 v[200:203], v149
	ds_read_b128 v[214:217], v149 offset:1024
	ds_read_b128 v[218:221], v149 offset:2048
	ds_read_b128 v[222:225], v149 offset:3072
	ds_read_b128 v[226:229], v149 offset:4096
	ds_read_b128 v[230:233], v149 offset:5120
	ds_read_b128 v[234:237], v149 offset:6144
	ds_read_b128 v[238:241], v149 offset:7168
	global_load_lds_dwordx4 v142, s[42:43]
	s_add_i32 m0, s25, 0xe000
	s_nop 0
	global_load_lds_dwordx4 v144, s[42:43]
	s_waitcnt vmcnt(8)
	s_waitcnt lgkmcnt(0)
	s_barrier
	s_setprio 1
	s_waitcnt lgkmcnt(0)
	v_mfma_f32_16x16x32_bf16 v[132:135], v[162:165], v[200:203], v[132:135]
	v_mfma_f32_16x16x32_bf16 v[128:131], v[170:173], v[200:203], v[128:131]
	v_mfma_f32_16x16x32_bf16 v[116:119], v[162:165], v[218:221], v[116:119]
	v_mfma_f32_16x16x32_bf16 v[112:115], v[170:173], v[218:221], v[112:115]
	v_mfma_f32_16x16x32_bf16 v[100:103], v[162:165], v[226:229], v[100:103]
	v_mfma_f32_16x16x32_bf16 v[96:99], v[170:173], v[226:229], v[96:99]
	v_mfma_f32_16x16x32_bf16 v[84:87], v[162:165], v[234:237], v[84:87]
	v_mfma_f32_16x16x32_bf16 v[80:83], v[170:173], v[234:237], v[80:83]
	v_mfma_f32_16x16x32_bf16 v[132:135], v[166:169], v[214:217], v[132:135]
	v_mfma_f32_16x16x32_bf16 v[128:131], v[174:177], v[214:217], v[128:131]
	v_mfma_f32_16x16x32_bf16 v[116:119], v[166:169], v[222:225], v[116:119]
	v_mfma_f32_16x16x32_bf16 v[112:115], v[174:177], v[222:225], v[112:115]
	v_mfma_f32_16x16x32_bf16 v[100:103], v[166:169], v[230:233], v[100:103]
	v_mfma_f32_16x16x32_bf16 v[96:99], v[174:177], v[230:233], v[96:99]
	v_mfma_f32_16x16x32_bf16 v[84:87], v[166:169], v[238:241], v[84:87]
	v_mfma_f32_16x16x32_bf16 v[80:83], v[174:177], v[238:241], v[80:83]
	s_setprio 0
	s_setprio 1
	v_mfma_f32_16x16x32_bf16 v[124:127], v[184:187], v[200:203], v[124:127]
	v_mfma_f32_16x16x32_bf16 v[120:123], v[192:195], v[200:203], v[120:123]
	v_mfma_f32_16x16x32_bf16 v[108:111], v[184:187], v[218:221], v[108:111]
	v_mfma_f32_16x16x32_bf16 v[104:107], v[192:195], v[218:221], v[104:107]
	v_mfma_f32_16x16x32_bf16 v[92:95], v[184:187], v[226:229], v[92:95]
	v_mfma_f32_16x16x32_bf16 v[88:91], v[192:195], v[226:229], v[88:91]
	v_mfma_f32_16x16x32_bf16 v[76:79], v[184:187], v[234:237], v[76:79]
	v_mfma_f32_16x16x32_bf16 v[72:75], v[192:195], v[234:237], v[72:75]
	v_mfma_f32_16x16x32_bf16 v[124:127], v[188:191], v[214:217], v[124:127]
	v_mfma_f32_16x16x32_bf16 v[120:123], v[196:199], v[214:217], v[120:123]
	v_mfma_f32_16x16x32_bf16 v[108:111], v[188:191], v[222:225], v[108:111]
	v_mfma_f32_16x16x32_bf16 v[104:107], v[196:199], v[222:225], v[104:107]
	v_mfma_f32_16x16x32_bf16 v[92:95], v[188:191], v[230:233], v[92:95]
	v_mfma_f32_16x16x32_bf16 v[88:91], v[196:199], v[230:233], v[88:91]
	v_mfma_f32_16x16x32_bf16 v[76:79], v[188:191], v[238:241], v[76:79]
	v_mfma_f32_16x16x32_bf16 v[72:75], v[196:199], v[238:241], v[72:75]
	s_setprio 0
	s_barrier
	s_add_u32 s98, s44, s22
	s_addc_u32 s99, s45, s23
	s_add_u32 s100, s46, s22
	s_addc_u32 s101, s47, s23
	s_add_i32 s64, s64, s20
	s_mov_b32 m0, s64
	ds_read_b128 v[200:203], v149 offset:16384
	ds_read_b128 v[214:217], v149 offset:17408
	ds_read_b128 v[218:221], v149 offset:18432
	ds_read_b128 v[222:225], v149 offset:19456
	ds_read_b128 v[226:229], v149 offset:20480
	ds_read_b128 v[230:233], v149 offset:21504
	ds_read_b128 v[234:237], v149 offset:22528
	ds_read_b128 v[238:241], v149 offset:23552
	global_load_lds_dwordx4 v34, s[44:45]
	s_add_i32 m0, s64, 0x2000
	s_add_u32 s64, s44, 0x80000
	s_addc_u32 s65, s45, 0
	s_add_i32 s67, s67, s20
	global_load_lds_dwordx4 v14, s[44:45]
	s_mov_b32 m0, s67
	global_load_lds_dwordx4 v34, s[64:65]
	s_add_i32 m0, s67, 0x2000
	s_nop 0
	global_load_lds_dwordx4 v14, s[64:65]
	s_mov_b32 m0, s25
	s_nop 0
	global_load_lds_dwordx4 v138, s[46:47]
	s_mov_b32 m0, s26
	s_nop 0
	global_load_lds_dwordx4 v136, s[46:47]
	s_waitcnt vmcnt(8)
	s_waitcnt lgkmcnt(0)
	s_barrier
	s_setprio 1
	s_waitcnt lgkmcnt(0)
	v_mfma_f32_16x16x32_bf16 v[68:71], v[162:165], v[200:203], v[68:71]
	v_mfma_f32_16x16x32_bf16 v[64:67], v[170:173], v[200:203], v[64:67]
	v_mfma_f32_16x16x32_bf16 v[52:55], v[162:165], v[218:221], v[52:55]
	v_mfma_f32_16x16x32_bf16 v[48:51], v[170:173], v[218:221], v[48:51]
	v_mfma_f32_16x16x32_bf16 v[36:39], v[162:165], v[226:229], v[36:39]
	v_mfma_f32_16x16x32_bf16 v[30:33], v[170:173], v[226:229], v[30:33]
	v_mfma_f32_16x16x32_bf16 v[18:21], v[162:165], v[234:237], v[18:21]
	v_mfma_f32_16x16x32_bf16 v[10:13], v[170:173], v[234:237], v[10:13]
	v_mfma_f32_16x16x32_bf16 v[68:71], v[166:169], v[214:217], v[68:71]
	v_mfma_f32_16x16x32_bf16 v[64:67], v[174:177], v[214:217], v[64:67]
	v_mfma_f32_16x16x32_bf16 v[52:55], v[166:169], v[222:225], v[52:55]
	v_mfma_f32_16x16x32_bf16 v[48:51], v[174:177], v[222:225], v[48:51]
	v_mfma_f32_16x16x32_bf16 v[36:39], v[166:169], v[230:233], v[36:39]
	v_mfma_f32_16x16x32_bf16 v[30:33], v[174:177], v[230:233], v[30:33]
	v_mfma_f32_16x16x32_bf16 v[18:21], v[166:169], v[238:241], v[18:21]
	v_mfma_f32_16x16x32_bf16 v[10:13], v[174:177], v[238:241], v[10:13]
	s_setprio 0
	s_setprio 1
	v_mfma_f32_16x16x32_bf16 v[60:63], v[184:187], v[200:203], v[60:63]
	v_mfma_f32_16x16x32_bf16 v[56:59], v[192:195], v[200:203], v[56:59]
	v_mfma_f32_16x16x32_bf16 v[44:47], v[184:187], v[218:221], v[44:47]
	v_mfma_f32_16x16x32_bf16 v[40:43], v[192:195], v[218:221], v[40:43]
	v_mfma_f32_16x16x32_bf16 v[26:29], v[184:187], v[226:229], v[26:29]
	v_mfma_f32_16x16x32_bf16 v[22:25], v[192:195], v[226:229], v[22:25]
	v_mfma_f32_16x16x32_bf16 v[6:9], v[184:187], v[234:237], v[6:9]
	v_mfma_f32_16x16x32_bf16 v[2:5], v[192:195], v[234:237], v[2:5]
	v_mfma_f32_16x16x32_bf16 v[60:63], v[188:191], v[214:217], v[60:63]
	v_mfma_f32_16x16x32_bf16 v[56:59], v[196:199], v[214:217], v[56:59]
	v_mfma_f32_16x16x32_bf16 v[44:47], v[188:191], v[222:225], v[44:47]
	v_mfma_f32_16x16x32_bf16 v[40:43], v[196:199], v[222:225], v[40:43]
	v_mfma_f32_16x16x32_bf16 v[26:29], v[188:191], v[230:233], v[26:29]
	v_mfma_f32_16x16x32_bf16 v[22:25], v[196:199], v[230:233], v[22:25]
	v_mfma_f32_16x16x32_bf16 v[6:9], v[188:191], v[238:241], v[6:9]
	v_mfma_f32_16x16x32_bf16 v[2:5], v[196:199], v[238:241], v[2:5]
	s_setprio 0
	s_barrier
	s_add_i32 s64, 0, 0x18000
	v_add_u32_e32 v151, s64, v141
	s_add_i32 s65, 0, 0x1c000
	ds_read_b128 v[162:165], v151
	ds_read_b128 v[166:169], v151 offset:1024
	ds_read_b128 v[170:173], v151 offset:2048
	ds_read_b128 v[174:177], v151 offset:3072
	v_add_u32_e32 v151, s65, v141
	ds_read_b128 v[184:187], v151
	ds_read_b128 v[188:191], v151 offset:1024
	ds_read_b128 v[192:195], v151 offset:2048
	ds_read_b128 v[196:199], v151 offset:3072
	s_add_u32 s46, s46, 0x80000
	s_addc_u32 s47, s47, 0
	s_mov_b32 m0, s27
	ds_read_b128 v[200:203], v149 offset:32768
	ds_read_b128 v[214:217], v149 offset:33792
	ds_read_b128 v[218:221], v149 offset:34816
	ds_read_b128 v[222:225], v149 offset:35840
	ds_read_b128 v[226:229], v149 offset:36864
	ds_read_b128 v[230:233], v149 offset:37888
	ds_read_b128 v[234:237], v149 offset:38912
	ds_read_b128 v[238:241], v149 offset:39936
	global_load_lds_dwordx4 v138, s[46:47]
	s_mov_b32 m0, s31
	s_nop 0
	global_load_lds_dwordx4 v136, s[46:47]
	s_waitcnt vmcnt(8)
	s_waitcnt lgkmcnt(0)
	s_barrier
	s_setprio 1
	s_waitcnt lgkmcnt(0)
	v_mfma_f32_16x16x32_bf16 v[132:135], v[162:165], v[200:203], v[132:135]
	v_mfma_f32_16x16x32_bf16 v[128:131], v[170:173], v[200:203], v[128:131]
	v_mfma_f32_16x16x32_bf16 v[116:119], v[162:165], v[218:221], v[116:119]
	v_mfma_f32_16x16x32_bf16 v[112:115], v[170:173], v[218:221], v[112:115]
	v_mfma_f32_16x16x32_bf16 v[100:103], v[162:165], v[226:229], v[100:103]
	v_mfma_f32_16x16x32_bf16 v[96:99], v[170:173], v[226:229], v[96:99]
	v_mfma_f32_16x16x32_bf16 v[84:87], v[162:165], v[234:237], v[84:87]
	v_mfma_f32_16x16x32_bf16 v[80:83], v[170:173], v[234:237], v[80:83]
	v_mfma_f32_16x16x32_bf16 v[132:135], v[166:169], v[214:217], v[132:135]
	v_mfma_f32_16x16x32_bf16 v[128:131], v[174:177], v[214:217], v[128:131]
	v_mfma_f32_16x16x32_bf16 v[116:119], v[166:169], v[222:225], v[116:119]
	v_mfma_f32_16x16x32_bf16 v[112:115], v[174:177], v[222:225], v[112:115]
	v_mfma_f32_16x16x32_bf16 v[100:103], v[166:169], v[230:233], v[100:103]
	v_mfma_f32_16x16x32_bf16 v[96:99], v[174:177], v[230:233], v[96:99]
	v_mfma_f32_16x16x32_bf16 v[84:87], v[166:169], v[238:241], v[84:87]
	v_mfma_f32_16x16x32_bf16 v[80:83], v[174:177], v[238:241], v[80:83]
	s_setprio 0
	s_setprio 1
	v_mfma_f32_16x16x32_bf16 v[124:127], v[184:187], v[200:203], v[124:127]
	v_mfma_f32_16x16x32_bf16 v[120:123], v[192:195], v[200:203], v[120:123]
	v_mfma_f32_16x16x32_bf16 v[108:111], v[184:187], v[218:221], v[108:111]
	v_mfma_f32_16x16x32_bf16 v[104:107], v[192:195], v[218:221], v[104:107]
	v_mfma_f32_16x16x32_bf16 v[92:95], v[184:187], v[226:229], v[92:95]
	v_mfma_f32_16x16x32_bf16 v[88:91], v[192:195], v[226:229], v[88:91]
	v_mfma_f32_16x16x32_bf16 v[76:79], v[184:187], v[234:237], v[76:79]
	v_mfma_f32_16x16x32_bf16 v[72:75], v[192:195], v[234:237], v[72:75]
	v_mfma_f32_16x16x32_bf16 v[124:127], v[188:191], v[214:217], v[124:127]
	v_mfma_f32_16x16x32_bf16 v[120:123], v[196:199], v[214:217], v[120:123]
	v_mfma_f32_16x16x32_bf16 v[108:111], v[188:191], v[222:225], v[108:111]
	v_mfma_f32_16x16x32_bf16 v[104:107], v[196:199], v[222:225], v[104:107]
	v_mfma_f32_16x16x32_bf16 v[92:95], v[188:191], v[230:233], v[92:95]
	v_mfma_f32_16x16x32_bf16 v[88:91], v[196:199], v[230:233], v[88:91]
	v_mfma_f32_16x16x32_bf16 v[76:79], v[188:191], v[238:241], v[76:79]
	v_mfma_f32_16x16x32_bf16 v[72:75], v[196:199], v[238:241], v[72:75]
	s_setprio 0
	s_barrier
	s_add_i32 s46, s64, s20
	s_mov_b32 m0, s46
	ds_read_b128 v[200:203], v149 offset:49152
	ds_read_b128 v[214:217], v149 offset:50176
	ds_read_b128 v[218:221], v149 offset:51200
	ds_read_b128 v[222:225], v149 offset:52224
	ds_read_b128 v[226:229], v149 offset:53248
	ds_read_b128 v[230:233], v149 offset:54272
	ds_read_b128 v[234:237], v149 offset:55296
	ds_read_b128 v[238:241], v149 offset:56320
	global_load_lds_dwordx4 v34, s[98:99]
	s_add_i32 m0, s46, 0x2000
	s_add_u32 s44, s44, 0x80080
	s_addc_u32 s45, s45, 0
	s_add_i32 s46, s65, s20
	global_load_lds_dwordx4 v14, s[98:99]
	s_mov_b32 m0, s46
	s_nop 0
	global_load_lds_dwordx4 v34, s[44:45]
	s_add_i32 m0, s46, 0x2000
	s_nop 0
	global_load_lds_dwordx4 v14, s[44:45]
	s_mov_b32 m0, s48
	s_nop 0
	global_load_lds_dwordx4 v138, s[100:101]
	s_mov_b32 m0, s49
	s_nop 0
	global_load_lds_dwordx4 v136, s[100:101]
	s_waitcnt vmcnt(8)
	s_waitcnt lgkmcnt(0)
	s_barrier
	s_setprio 1
	s_waitcnt lgkmcnt(0)
	v_mfma_f32_16x16x32_bf16 v[68:71], v[162:165], v[200:203], v[68:71]
	v_mfma_f32_16x16x32_bf16 v[64:67], v[170:173], v[200:203], v[64:67]
	v_mfma_f32_16x16x32_bf16 v[52:55], v[162:165], v[218:221], v[52:55]
	v_mfma_f32_16x16x32_bf16 v[48:51], v[170:173], v[218:221], v[48:51]
	v_mfma_f32_16x16x32_bf16 v[36:39], v[162:165], v[226:229], v[36:39]
	v_mfma_f32_16x16x32_bf16 v[30:33], v[170:173], v[226:229], v[30:33]
	v_mfma_f32_16x16x32_bf16 v[18:21], v[162:165], v[234:237], v[18:21]
	v_mfma_f32_16x16x32_bf16 v[10:13], v[170:173], v[234:237], v[10:13]
	v_mfma_f32_16x16x32_bf16 v[68:71], v[166:169], v[214:217], v[68:71]
	v_mfma_f32_16x16x32_bf16 v[64:67], v[174:177], v[214:217], v[64:67]
	v_mfma_f32_16x16x32_bf16 v[52:55], v[166:169], v[222:225], v[52:55]
	v_mfma_f32_16x16x32_bf16 v[48:51], v[174:177], v[222:225], v[48:51]
	v_mfma_f32_16x16x32_bf16 v[36:39], v[166:169], v[230:233], v[36:39]
	v_mfma_f32_16x16x32_bf16 v[30:33], v[174:177], v[230:233], v[30:33]
	v_mfma_f32_16x16x32_bf16 v[18:21], v[166:169], v[238:241], v[18:21]
	v_mfma_f32_16x16x32_bf16 v[10:13], v[174:177], v[238:241], v[10:13]
	s_setprio 0
	s_setprio 1
	v_mfma_f32_16x16x32_bf16 v[60:63], v[184:187], v[200:203], v[60:63]
	v_mfma_f32_16x16x32_bf16 v[56:59], v[192:195], v[200:203], v[56:59]
	v_mfma_f32_16x16x32_bf16 v[44:47], v[184:187], v[218:221], v[44:47]
	v_mfma_f32_16x16x32_bf16 v[40:43], v[192:195], v[218:221], v[40:43]
	v_mfma_f32_16x16x32_bf16 v[26:29], v[184:187], v[226:229], v[26:29]
	v_mfma_f32_16x16x32_bf16 v[22:25], v[192:195], v[226:229], v[22:25]
	v_mfma_f32_16x16x32_bf16 v[6:9], v[184:187], v[234:237], v[6:9]
	v_mfma_f32_16x16x32_bf16 v[2:5], v[192:195], v[234:237], v[2:5]
	v_mfma_f32_16x16x32_bf16 v[60:63], v[188:191], v[214:217], v[60:63]
	v_mfma_f32_16x16x32_bf16 v[56:59], v[196:199], v[214:217], v[56:59]
	v_mfma_f32_16x16x32_bf16 v[44:47], v[188:191], v[222:225], v[44:47]
	v_mfma_f32_16x16x32_bf16 v[40:43], v[196:199], v[222:225], v[40:43]
	v_mfma_f32_16x16x32_bf16 v[26:29], v[188:191], v[230:233], v[26:29]
	v_mfma_f32_16x16x32_bf16 v[22:25], v[196:199], v[230:233], v[22:25]
	v_mfma_f32_16x16x32_bf16 v[6:9], v[188:191], v[238:241], v[6:9]
	v_mfma_f32_16x16x32_bf16 v[2:5], v[196:199], v[238:241], v[2:5]
	s_setprio 0
	s_barrier
	s_add_i32 s61, s61, 2
	s_add_u32 s42, s42, 0x100
	s_addc_u32 s43, s43, 0
	s_add_u32 s55, s55, 0x100
	s_addc_u32 s60, s60, 0
	s_cmp_gt_u32 s61, 29
	s_cbranch_scc0 .LBB0_1664
	s_and_b64 vcc, exec, s[10:11]
	s_cbranch_vccz .LBB0_1667
	s_barrier

.LBB0_1764:
	s_add_i32 vcc_lo, s44, 2
	s_add_u32 s42, s36, 0x100
	s_addc_u32 s43, s37, 0
	s_add_i32 s72, 0, 0x10000
	s_cmp_eq_u32 s11, s44
	s_cselect_b32 s47, s13, s43
	s_cselect_b32 s46, s12, s42
	s_cselect_b32 s45, s29, s71
	s_cselect_b32 s44, s28, s70
	s_add_i32 s73, 0, 0x14000
	v_add_u32_e32 v160, s72, v152
	v_add_u32_e32 v176, s73, v152
	ds_read_b128 v[136:139], v160
	ds_read_b128 v[148:151], v160 offset:1024
	ds_read_b128 v[156:159], v160 offset:2048
	ds_read_b128 v[160:163], v160 offset:3072
	ds_read_b128 v[164:167], v176
	ds_read_b128 v[168:171], v176 offset:1024
	ds_read_b128 v[172:175], v176 offset:2048
	ds_read_b128 v[184:187], v176 offset:3072
	s_add_i32 m0, s25, 0xc000
	ds_read_b128 v[188:191], v155
	ds_read_b128 v[192:195], v155 offset:1024
	ds_read_b128 v[196:199], v155 offset:2048
	ds_read_b128 v[200:203], v155 offset:3072
	ds_read_b128 v[214:217], v155 offset:4096
	ds_read_b128 v[218:221], v155 offset:5120
	ds_read_b128 v[222:225], v155 offset:6144
	ds_read_b128 v[226:229], v155 offset:7168
	global_load_lds_dwordx4 v144, s[36:37]
	s_add_i32 m0, s25, 0xe000
	s_nop 0
	global_load_lds_dwordx4 v146, s[36:37]
	s_waitcnt vmcnt(8)
	s_waitcnt lgkmcnt(0)
	s_barrier
	s_setprio 1
	s_waitcnt lgkmcnt(0)
	v_mfma_f32_16x16x32_bf16 v[132:135], v[136:139], v[188:191], v[132:135]
	v_mfma_f32_16x16x32_bf16 v[128:131], v[156:159], v[188:191], v[128:131]
	v_mfma_f32_16x16x32_bf16 v[116:119], v[136:139], v[196:199], v[116:119]
	v_mfma_f32_16x16x32_bf16 v[112:115], v[156:159], v[196:199], v[112:115]
	v_mfma_f32_16x16x32_bf16 v[100:103], v[136:139], v[214:217], v[100:103]
	v_mfma_f32_16x16x32_bf16 v[96:99], v[156:159], v[214:217], v[96:99]
	v_mfma_f32_16x16x32_bf16 v[84:87], v[136:139], v[222:225], v[84:87]
	v_mfma_f32_16x16x32_bf16 v[80:83], v[156:159], v[222:225], v[80:83]
	v_mfma_f32_16x16x32_bf16 v[132:135], v[148:151], v[192:195], v[132:135]
	v_mfma_f32_16x16x32_bf16 v[128:131], v[160:163], v[192:195], v[128:131]
	v_mfma_f32_16x16x32_bf16 v[116:119], v[148:151], v[200:203], v[116:119]
	v_mfma_f32_16x16x32_bf16 v[112:115], v[160:163], v[200:203], v[112:115]
	v_mfma_f32_16x16x32_bf16 v[100:103], v[148:151], v[218:221], v[100:103]
	v_mfma_f32_16x16x32_bf16 v[96:99], v[160:163], v[218:221], v[96:99]
	v_mfma_f32_16x16x32_bf16 v[84:87], v[148:151], v[226:229], v[84:87]
	v_mfma_f32_16x16x32_bf16 v[80:83], v[160:163], v[226:229], v[80:83]
	s_setprio 0
	s_setprio 1
	v_mfma_f32_16x16x32_bf16 v[124:127], v[164:167], v[188:191], v[124:127]
	v_mfma_f32_16x16x32_bf16 v[120:123], v[172:175], v[188:191], v[120:123]
	v_mfma_f32_16x16x32_bf16 v[108:111], v[164:167], v[196:199], v[108:111]
	v_mfma_f32_16x16x32_bf16 v[104:107], v[172:175], v[196:199], v[104:107]
	v_mfma_f32_16x16x32_bf16 v[92:95], v[164:167], v[214:217], v[92:95]
	v_mfma_f32_16x16x32_bf16 v[88:91], v[172:175], v[214:217], v[88:91]
	v_mfma_f32_16x16x32_bf16 v[76:79], v[164:167], v[222:225], v[76:79]
	v_mfma_f32_16x16x32_bf16 v[72:75], v[172:175], v[222:225], v[72:75]
	v_mfma_f32_16x16x32_bf16 v[124:127], v[168:171], v[192:195], v[124:127]
	v_mfma_f32_16x16x32_bf16 v[120:123], v[184:187], v[192:195], v[120:123]
	v_mfma_f32_16x16x32_bf16 v[108:111], v[168:171], v[200:203], v[108:111]
	v_mfma_f32_16x16x32_bf16 v[104:107], v[184:187], v[200:203], v[104:107]
	v_mfma_f32_16x16x32_bf16 v[92:95], v[168:171], v[218:221], v[92:95]
	v_mfma_f32_16x16x32_bf16 v[88:91], v[184:187], v[218:221], v[88:91]
	v_mfma_f32_16x16x32_bf16 v[76:79], v[168:171], v[226:229], v[76:79]
	v_mfma_f32_16x16x32_bf16 v[72:75], v[184:187], v[226:229], v[72:75]
	s_setprio 0
	s_barrier
	s_add_u32 s98, s44, s22
	s_addc_u32 s99, s45, s23
	s_add_u32 s100, s46, s22
	s_addc_u32 s101, s47, s23
	s_add_i32 s36, s72, s20
	s_mov_b32 m0, s36
	ds_read_b128 v[188:191], v155 offset:16384
	ds_read_b128 v[192:195], v155 offset:17408
	ds_read_b128 v[196:199], v155 offset:18432
	ds_read_b128 v[200:203], v155 offset:19456
	ds_read_b128 v[214:217], v155 offset:20480
	ds_read_b128 v[218:221], v155 offset:21504
	ds_read_b128 v[222:225], v155 offset:22528
	ds_read_b128 v[226:229], v155 offset:23552
	global_load_lds_dwordx4 v34, s[44:45]
	s_add_i32 m0, s36, 0x2000
	s_add_u32 s36, s44, 0x160000
	s_addc_u32 s37, s45, 0
	s_add_i32 s72, s73, s20
	global_load_lds_dwordx4 v142, s[44:45]
	s_mov_b32 m0, s72
	global_load_lds_dwordx4 v34, s[36:37]
	s_add_i32 m0, s72, 0x2000
	s_nop 0
	global_load_lds_dwordx4 v142, s[36:37]
	s_mov_b32 m0, s25
	s_nop 0
	global_load_lds_dwordx4 v14, s[46:47]
	s_mov_b32 m0, s26
	s_nop 0
	global_load_lds_dwordx4 v140, s[46:47]
	s_waitcnt vmcnt(8)
	s_waitcnt lgkmcnt(0)
	s_barrier
	s_setprio 1
	s_waitcnt lgkmcnt(0)
	v_mfma_f32_16x16x32_bf16 v[68:71], v[136:139], v[188:191], v[68:71]
	v_mfma_f32_16x16x32_bf16 v[64:67], v[156:159], v[188:191], v[64:67]
	v_mfma_f32_16x16x32_bf16 v[52:55], v[136:139], v[196:199], v[52:55]
	v_mfma_f32_16x16x32_bf16 v[48:51], v[156:159], v[196:199], v[48:51]
	v_mfma_f32_16x16x32_bf16 v[36:39], v[136:139], v[214:217], v[36:39]
	v_mfma_f32_16x16x32_bf16 v[30:33], v[156:159], v[214:217], v[30:33]
	v_mfma_f32_16x16x32_bf16 v[18:21], v[136:139], v[222:225], v[18:21]
	v_mfma_f32_16x16x32_bf16 v[10:13], v[156:159], v[222:225], v[10:13]
	v_mfma_f32_16x16x32_bf16 v[68:71], v[148:151], v[192:195], v[68:71]
	v_mfma_f32_16x16x32_bf16 v[64:67], v[160:163], v[192:195], v[64:67]
	v_mfma_f32_16x16x32_bf16 v[52:55], v[148:151], v[200:203], v[52:55]
	v_mfma_f32_16x16x32_bf16 v[48:51], v[160:163], v[200:203], v[48:51]
	v_mfma_f32_16x16x32_bf16 v[36:39], v[148:151], v[218:221], v[36:39]
	v_mfma_f32_16x16x32_bf16 v[30:33], v[160:163], v[218:221], v[30:33]
	v_mfma_f32_16x16x32_bf16 v[18:21], v[148:151], v[226:229], v[18:21]
	v_mfma_f32_16x16x32_bf16 v[10:13], v[160:163], v[226:229], v[10:13]
	s_setprio 0
	s_setprio 1
	v_mfma_f32_16x16x32_bf16 v[60:63], v[164:167], v[188:191], v[60:63]
	v_mfma_f32_16x16x32_bf16 v[56:59], v[172:175], v[188:191], v[56:59]
	v_mfma_f32_16x16x32_bf16 v[44:47], v[164:167], v[196:199], v[44:47]
	v_mfma_f32_16x16x32_bf16 v[40:43], v[172:175], v[196:199], v[40:43]
	v_mfma_f32_16x16x32_bf16 v[26:29], v[164:167], v[214:217], v[26:29]
	v_mfma_f32_16x16x32_bf16 v[22:25], v[172:175], v[214:217], v[22:25]
	v_mfma_f32_16x16x32_bf16 v[6:9], v[164:167], v[222:225], v[6:9]
	v_mfma_f32_16x16x32_bf16 v[2:5], v[172:175], v[222:225], v[2:5]
	v_mfma_f32_16x16x32_bf16 v[60:63], v[168:171], v[192:195], v[60:63]
	v_mfma_f32_16x16x32_bf16 v[56:59], v[184:187], v[192:195], v[56:59]
	v_mfma_f32_16x16x32_bf16 v[44:47], v[168:171], v[200:203], v[44:47]
	v_mfma_f32_16x16x32_bf16 v[40:43], v[184:187], v[200:203], v[40:43]
	v_mfma_f32_16x16x32_bf16 v[26:29], v[168:171], v[218:221], v[26:29]
	v_mfma_f32_16x16x32_bf16 v[22:25], v[184:187], v[218:221], v[22:25]
	v_mfma_f32_16x16x32_bf16 v[6:9], v[168:171], v[226:229], v[6:9]
	v_mfma_f32_16x16x32_bf16 v[2:5], v[184:187], v[226:229], v[2:5]
	s_setprio 0
	s_barrier
	s_add_i32 s72, 0, 0x18000
	s_add_i32 s73, 0, 0x1c000
	v_add_u32_e32 v160, s72, v152
	v_add_u32_e32 v183, s73, v152
	ds_read_b128 v[136:139], v160
	ds_read_b128 v[148:151], v160 offset:1024
	ds_read_b128 v[156:159], v160 offset:2048
	ds_read_b128 v[160:163], v160 offset:3072
	ds_read_b128 v[164:167], v183
	ds_read_b128 v[168:171], v183 offset:1024
	ds_read_b128 v[172:175], v183 offset:2048
	ds_read_b128 v[184:187], v183 offset:3072
	s_add_u32 s36, s46, 0x160000
	s_addc_u32 s37, s47, 0
	s_mov_b32 m0, s27
	ds_read_b128 v[188:191], v155 offset:32768
	ds_read_b128 v[192:195], v155 offset:33792
	ds_read_b128 v[196:199], v155 offset:34816
	ds_read_b128 v[200:203], v155 offset:35840
	ds_read_b128 v[214:217], v155 offset:36864
	ds_read_b128 v[218:221], v155 offset:37888
	ds_read_b128 v[222:225], v155 offset:38912
	ds_read_b128 v[226:229], v155 offset:39936
	global_load_lds_dwordx4 v14, s[36:37]
	s_mov_b32 m0, s31
	s_nop 0
	global_load_lds_dwordx4 v140, s[36:37]
	s_waitcnt vmcnt(8)
	s_waitcnt lgkmcnt(0)
	s_barrier
	s_setprio 1
	s_waitcnt lgkmcnt(0)
	v_mfma_f32_16x16x32_bf16 v[132:135], v[136:139], v[188:191], v[132:135]
	v_mfma_f32_16x16x32_bf16 v[128:131], v[156:159], v[188:191], v[128:131]
	v_mfma_f32_16x16x32_bf16 v[116:119], v[136:139], v[196:199], v[116:119]
	v_mfma_f32_16x16x32_bf16 v[112:115], v[156:159], v[196:199], v[112:115]
	v_mfma_f32_16x16x32_bf16 v[100:103], v[136:139], v[214:217], v[100:103]
	v_mfma_f32_16x16x32_bf16 v[96:99], v[156:159], v[214:217], v[96:99]
	v_mfma_f32_16x16x32_bf16 v[84:87], v[136:139], v[222:225], v[84:87]
	v_mfma_f32_16x16x32_bf16 v[80:83], v[156:159], v[222:225], v[80:83]
	v_mfma_f32_16x16x32_bf16 v[132:135], v[148:151], v[192:195], v[132:135]
	v_mfma_f32_16x16x32_bf16 v[128:131], v[160:163], v[192:195], v[128:131]
	v_mfma_f32_16x16x32_bf16 v[116:119], v[148:151], v[200:203], v[116:119]
	v_mfma_f32_16x16x32_bf16 v[112:115], v[160:163], v[200:203], v[112:115]
	v_mfma_f32_16x16x32_bf16 v[100:103], v[148:151], v[218:221], v[100:103]
	v_mfma_f32_16x16x32_bf16 v[96:99], v[160:163], v[218:221], v[96:99]
	v_mfma_f32_16x16x32_bf16 v[84:87], v[148:151], v[226:229], v[84:87]
	v_mfma_f32_16x16x32_bf16 v[80:83], v[160:163], v[226:229], v[80:83]
	s_setprio 0
	s_setprio 1
	v_mfma_f32_16x16x32_bf16 v[124:127], v[164:167], v[188:191], v[124:127]
	v_mfma_f32_16x16x32_bf16 v[120:123], v[172:175], v[188:191], v[120:123]
	v_mfma_f32_16x16x32_bf16 v[108:111], v[164:167], v[196:199], v[108:111]
	v_mfma_f32_16x16x32_bf16 v[104:107], v[172:175], v[196:199], v[104:107]
	v_mfma_f32_16x16x32_bf16 v[92:95], v[164:167], v[214:217], v[92:95]
	v_mfma_f32_16x16x32_bf16 v[88:91], v[172:175], v[214:217], v[88:91]
	v_mfma_f32_16x16x32_bf16 v[76:79], v[164:167], v[222:225], v[76:79]
	v_mfma_f32_16x16x32_bf16 v[72:75], v[172:175], v[222:225], v[72:75]
	v_mfma_f32_16x16x32_bf16 v[124:127], v[168:171], v[192:195], v[124:127]
	v_mfma_f32_16x16x32_bf16 v[120:123], v[184:187], v[192:195], v[120:123]
	v_mfma_f32_16x16x32_bf16 v[108:111], v[168:171], v[200:203], v[108:111]
	v_mfma_f32_16x16x32_bf16 v[104:107], v[184:187], v[200:203], v[104:107]
	v_mfma_f32_16x16x32_bf16 v[92:95], v[168:171], v[218:221], v[92:95]
	v_mfma_f32_16x16x32_bf16 v[88:91], v[184:187], v[218:221], v[88:91]
	v_mfma_f32_16x16x32_bf16 v[76:79], v[168:171], v[226:229], v[76:79]
	v_mfma_f32_16x16x32_bf16 v[72:75], v[184:187], v[226:229], v[72:75]
	s_setprio 0
	s_barrier
	s_add_i32 s36, s72, s20
	s_mov_b32 m0, s36
	ds_read_b128 v[188:191], v155 offset:49152
	ds_read_b128 v[192:195], v155 offset:50176
	ds_read_b128 v[196:199], v155 offset:51200
	ds_read_b128 v[200:203], v155 offset:52224
	ds_read_b128 v[214:217], v155 offset:53248
	ds_read_b128 v[218:221], v155 offset:54272
	ds_read_b128 v[222:225], v155 offset:55296
	ds_read_b128 v[226:229], v155 offset:56320
	global_load_lds_dwordx4 v34, s[98:99]
	s_add_i32 m0, s36, 0x2000
	s_add_u32 s36, s44, 0x160080
	s_addc_u32 s37, s45, 0
	s_add_i32 s44, s73, s20
	global_load_lds_dwordx4 v142, s[98:99]
	s_mov_b32 m0, s44
	s_nop 0
	global_load_lds_dwordx4 v34, s[36:37]
	s_add_i32 m0, s44, 0x2000
	s_nop 0
	global_load_lds_dwordx4 v142, s[36:37]
	s_mov_b32 m0, s50
	s_nop 0
	global_load_lds_dwordx4 v14, s[100:101]
	s_mov_b32 m0, s51
	s_nop 0
	global_load_lds_dwordx4 v140, s[100:101]
	s_waitcnt vmcnt(8)
	s_waitcnt lgkmcnt(0)
	s_barrier
	s_setprio 1
	s_waitcnt lgkmcnt(0)
	v_mfma_f32_16x16x32_bf16 v[68:71], v[136:139], v[188:191], v[68:71]
	v_mfma_f32_16x16x32_bf16 v[64:67], v[156:159], v[188:191], v[64:67]
	v_mfma_f32_16x16x32_bf16 v[52:55], v[136:139], v[196:199], v[52:55]
	v_mfma_f32_16x16x32_bf16 v[48:51], v[156:159], v[196:199], v[48:51]
	v_mfma_f32_16x16x32_bf16 v[36:39], v[136:139], v[214:217], v[36:39]
	v_mfma_f32_16x16x32_bf16 v[30:33], v[156:159], v[214:217], v[30:33]
	v_mfma_f32_16x16x32_bf16 v[18:21], v[136:139], v[222:225], v[18:21]
	v_mfma_f32_16x16x32_bf16 v[10:13], v[156:159], v[222:225], v[10:13]
	v_mfma_f32_16x16x32_bf16 v[68:71], v[148:151], v[192:195], v[68:71]
	v_mfma_f32_16x16x32_bf16 v[64:67], v[160:163], v[192:195], v[64:67]
	v_mfma_f32_16x16x32_bf16 v[52:55], v[148:151], v[200:203], v[52:55]
	v_mfma_f32_16x16x32_bf16 v[48:51], v[160:163], v[200:203], v[48:51]
	v_mfma_f32_16x16x32_bf16 v[36:39], v[148:151], v[218:221], v[36:39]
	v_mfma_f32_16x16x32_bf16 v[30:33], v[160:163], v[218:221], v[30:33]
	v_mfma_f32_16x16x32_bf16 v[18:21], v[148:151], v[226:229], v[18:21]
	v_mfma_f32_16x16x32_bf16 v[10:13], v[160:163], v[226:229], v[10:13]
	s_setprio 0
	s_setprio 1
	v_mfma_f32_16x16x32_bf16 v[60:63], v[164:167], v[188:191], v[60:63]
	v_mfma_f32_16x16x32_bf16 v[56:59], v[172:175], v[188:191], v[56:59]
	v_mfma_f32_16x16x32_bf16 v[44:47], v[164:167], v[196:199], v[44:47]
	v_mfma_f32_16x16x32_bf16 v[40:43], v[172:175], v[196:199], v[40:43]
	v_mfma_f32_16x16x32_bf16 v[26:29], v[164:167], v[214:217], v[26:29]
	v_mfma_f32_16x16x32_bf16 v[22:25], v[172:175], v[214:217], v[22:25]
	v_mfma_f32_16x16x32_bf16 v[6:9], v[164:167], v[222:225], v[6:9]
	v_mfma_f32_16x16x32_bf16 v[2:5], v[172:175], v[222:225], v[2:5]
	v_mfma_f32_16x16x32_bf16 v[60:63], v[168:171], v[192:195], v[60:63]
	v_mfma_f32_16x16x32_bf16 v[56:59], v[184:187], v[192:195], v[56:59]
	v_mfma_f32_16x16x32_bf16 v[44:47], v[168:171], v[200:203], v[44:47]
	v_mfma_f32_16x16x32_bf16 v[40:43], v[184:187], v[200:203], v[40:43]
	v_mfma_f32_16x16x32_bf16 v[26:29], v[168:171], v[218:221], v[26:29]
	v_mfma_f32_16x16x32_bf16 v[22:25], v[184:187], v[218:221], v[22:25]
	v_mfma_f32_16x16x32_bf16 v[6:9], v[168:171], v[226:229], v[6:9]
	v_mfma_f32_16x16x32_bf16 v[2:5], v[184:187], v[226:229], v[2:5]
	s_setprio 0
	s_barrier
	s_add_u32 s70, s70, 0x100
	s_addc_u32 s71, s71, 0
	s_cmp_ge_i32 vcc_lo, s67
	s_mov_b64 s[36:37], s[42:43]
	s_mov_b32 s44, vcc_lo
	s_cbranch_scc0 .LBB0_1764
	s_mov_b32 s71, 0x200000
	s_and_b64 vcc, exec, s[8:9]
	s_cbranch_vccz .LBB0_1767

	.amdhsa_kernel _Z3fwd4Args
		.amdhsa_group_segment_fixed_size 0
		.amdhsa_private_segment_fixed_size 0
		.amdhsa_kernarg_size 464
		.amdhsa_user_sgpr_count 2
		.amdhsa_user_sgpr_dispatch_ptr 0
		.amdhsa_user_sgpr_queue_ptr 0
		.amdhsa_user_sgpr_kernarg_segment_ptr 1
		.amdhsa_user_sgpr_dispatch_id 0
		.amdhsa_user_sgpr_kernarg_preload_length 0
		.amdhsa_user_sgpr_kernarg_preload_offset 0
		.amdhsa_user_sgpr_private_segment_size 0
		.amdhsa_uses_dynamic_stack 0
		.amdhsa_enable_private_segment 0
		.amdhsa_system_sgpr_workgroup_id_x 1
		.amdhsa_system_sgpr_workgroup_id_y 0
		.amdhsa_system_sgpr_workgroup_id_z 0
		.amdhsa_system_sgpr_workgroup_info 0
		.amdhsa_system_vgpr_workitem_id 0
		.amdhsa_next_free_vgpr 256
		.amdhsa_next_free_sgpr 102
		.amdhsa_accum_offset 256
		.amdhsa_reserve_vcc 1
		.amdhsa_float_round_mode_32 0
		.amdhsa_float_round_mode_16_64 0
		.amdhsa_float_denorm_mode_32 3
		.amdhsa_float_denorm_mode_16_64 3
		.amdhsa_dx10_clamp 1
		.amdhsa_ieee_mode 1
		.amdhsa_fp16_overflow 0
		.amdhsa_tg_split 0
		.amdhsa_exception_fp_ieee_invalid_op 0
		.amdhsa_exception_fp_denorm_src 0
		.amdhsa_exception_fp_ieee_div_zero 0
		.amdhsa_exception_fp_ieee_overflow 0
		.amdhsa_exception_fp_ieee_underflow 0
		.amdhsa_exception_fp_ieee_inexact 0
		.amdhsa_exception_int_div_zero 0
	.end_amdhsa_kernel

amdhsa.kernels:
  - .agpr_count:     0
    .args:
      - .offset:         0
        .size:           208
        .value_kind:     by_value
      - .offset:         208
        .size:           4
        .value_kind:     hidden_block_count_x
      - .offset:         212
        .size:           4
        .value_kind:     hidden_block_count_y
      - .offset:         216
        .size:           4
        .value_kind:     hidden_block_count_z
      - .offset:         220
        .size:           2
        .value_kind:     hidden_group_size_x
      - .offset:         222
        .size:           2
        .value_kind:     hidden_group_size_y
      - .offset:         224
        .size:           2
        .value_kind:     hidden_group_size_z
      - .offset:         226
        .size:           2
        .value_kind:     hidden_remainder_x
      - .offset:         228
        .size:           2
        .value_kind:     hidden_remainder_y
      - .offset:         230
        .size:           2
        .value_kind:     hidden_remainder_z
      - .offset:         248
        .size:           8
        .value_kind:     hidden_global_offset_x
      - .offset:         256
        .size:           8
        .value_kind:     hidden_global_offset_y
      - .offset:         264
        .size:           8
        .value_kind:     hidden_global_offset_z
      - .offset:         272
        .size:           2
        .value_kind:     hidden_grid_dims
      - .offset:         328
        .size:           4
        .value_kind:     hidden_dynamic_lds_size
    .group_segment_fixed_size: 0
    .kernarg_segment_align: 8
    .kernarg_segment_size: 464
    .language:       OpenCL C
    .language_version:
      - 2
      - 0
    .max_flat_workgroup_size: 512
    .name:           _Z3fwd4Args
    .private_segment_fixed_size: 0
    .sgpr_count:     108
    .sgpr_spill_count: 125
    .symbol:         _Z3fwd4Args.kd
    .uniform_work_group_size: 1
    .uses_dynamic_stack: false
    .vgpr_count:     256
    .vgpr_spill_count: 0
    .wavefront_size: 64
